# top-k threshold count loops: compares software-pipelined over 3 SGPR pairs, hazard s_nops removed
# speedup vs baseline: 1.0487x; 1.0068x over previous
; DI int wave_isum(int v) {
;   v += __builtin_amdgcn_update_dpp(0, v, 0xB1, 0xf, 0xf, true);
;   v += __builtin_amdgcn_update_dpp(0, v, 0x4E, 0xf, 0xf, true);
;   v += __builtin_amdgcn_update_dpp(0, v, 0x141, 0xf, 0xf, true);
;   v += __builtin_amdgcn_update_dpp(0, v, 0x140, 0xf, 0xf, true);
;   return __builtin_amdgcn_readlane(v, 0) + __builtin_amdgcn_readlane(v, 16) + __builtin_amdgcn_readlane(v, 32) + __builtin_amdgcn_readlane(v, 48);
; }
; template <int NJ>
; DI void b1_select(const float* sc, int nj, unsigned* mo) {
;     ...
;     for (int i = 0; i < 8; ++i) {
;       const unsigned cand = E << 23;
;       int c0 = 0, c1 = 0;
; #pragma unroll
;       for (int j = 0; j < NJ; ++j) { if (j & 1) c1 += (key[j] >= cand) ? 1 : 0; else c0 += (key[j] >= cand) ? 1 : 0; }
;       const int cnt = wave_isum(c0 + c1);
;       if (cnt >= 256) { T = cand; bit = 22; exact = (cnt == 256); break; }
;       if (E == 0u) break;
;       --E;
;     }
;   }
.LBB0_503:
	s_lshl_b32 s8, s7, 23
	v_cmp_le_u32_e32 vcc, s8, v2
	s_mov_b64 s[4:5], -1
	s_nop 0
	v_cndmask_b32_e64 v31, 0, 1, vcc
	v_cmp_le_u32_e32 vcc, s8, v7
	v_cmp_le_u32_e64 s[98:99], s8, v3
	v_cmp_le_u32_e64 s[100:101], s8, v9
	v_cndmask_b32_e64 v32, 0, 1, vcc
	v_cmp_le_u32_e32 vcc, s8, v6
	v_cndmask_b32_e64 v33, 0, 1, s[98:99]
	v_cmp_le_u32_e64 s[98:99], s8, v13
	v_cndmask_b32_e64 v34, 0, 1, s[100:101]
	v_cmp_le_u32_e64 s[100:101], s8, v10
	v_cndmask_b32_e64 v35, 0, 1, vcc
	v_cmp_le_u32_e32 vcc, s8, v17
	v_cndmask_b32_e64 v36, 0, 1, s[98:99]
	v_cmp_le_u32_e64 s[98:99], s8, v14
	v_cndmask_b32_e64 v37, 0, 1, s[100:101]
	v_cmp_le_u32_e64 s[100:101], s8, v21
	v_cndmask_b32_e64 v38, 0, 1, vcc
	v_cmp_le_u32_e32 vcc, s8, v18
	v_cndmask_b32_e64 v39, 0, 1, s[98:99]
	v_cmp_le_u32_e64 s[98:99], s8, v25
	v_cndmask_b32_e64 v40, 0, 1, s[100:101]
	v_cmp_le_u32_e64 s[100:101], s8, v22
	v_cndmask_b32_e64 v41, 0, 1, vcc
	v_cmp_le_u32_e32 vcc, s8, v27
	v_cndmask_b32_e64 v42, 0, 1, s[98:99]
	v_cmp_le_u32_e64 s[98:99], s8, v5
	v_cndmask_b32_e64 v43, 0, 1, s[100:101]
	v_cmp_le_u32_e64 s[100:101], s8, v11
	v_cndmask_b32_e64 v44, 0, 1, vcc
	v_cmp_le_u32_e32 vcc, s8, v15
	v_addc_co_u32_e64 v32, s[98:99], 0, v32, s[98:99]
	v_cmp_le_u32_e64 s[98:99], s8, v19
	v_addc_co_u32_e64 v32, s[100:101], v32, v34, s[100:101]
	v_cmp_le_u32_e64 s[100:101], s8, v23
	v_addc_co_u32_e32 v32, vcc, v32, v36, vcc
	v_cmp_le_u32_e32 vcc, s8, v26
	v_addc_co_u32_e64 v32, s[98:99], v32, v38, s[98:99]
	v_cmp_le_u32_e64 s[98:99], s8, v28
	v_addc_co_u32_e64 v32, s[100:101], v32, v40, s[100:101]
	v_cmp_le_u32_e64 s[100:101], s8, v29
	v_addc_co_u32_e32 v32, vcc, v32, v42, vcc
	v_cmp_le_u32_e32 vcc, s8, v4
	v_addc_co_u32_e64 v32, s[98:99], v32, v44, s[98:99]
	v_cmp_le_u32_e64 s[98:99], s8, v8
	v_addc_co_u32_e64 v31, s[100:101], v32, v31, s[100:101]
	v_cmp_le_u32_e64 s[100:101], s8, v12
	v_addc_co_u32_e32 v31, vcc, v31, v33, vcc
	v_cmp_le_u32_e32 vcc, s8, v16
	v_addc_co_u32_e64 v31, s[98:99], v31, v35, s[98:99]
	v_cmp_le_u32_e64 s[98:99], s8, v20
	v_addc_co_u32_e64 v31, s[100:101], v31, v37, s[100:101]
	v_cmp_le_u32_e64 s[100:101], s8, v24
	v_addc_co_u32_e32 v31, vcc, v31, v39, vcc
	v_addc_co_u32_e64 v31, s[98:99], v31, v41, s[98:99]
	v_addc_co_u32_e64 v31, s[100:101], v31, v43, s[100:101]
	s_nop 1
	v_add_u32_dpp v31, v31, v31 quad_perm:[1,0,3,2] row_mask:0xf bank_mask:0xf bound_ctrl:1
	s_nop 1
	v_add_u32_dpp v31, v31, v31 quad_perm:[2,3,0,1] row_mask:0xf bank_mask:0xf bound_ctrl:1
	s_nop 1
	v_add_u32_dpp v31, v31, v31 row_half_mirror row_mask:0xf bank_mask:0xf bound_ctrl:1
	s_nop 1
	v_add_u32_dpp v31, v31, v31 row_mirror row_mask:0xf bank_mask:0xf bound_ctrl:1
	s_nop 0
	v_readlane_b32 s2, v31, 0
	v_readlane_b32 s3, v31, 16
	s_add_i32 s2, s3, s2
	v_readlane_b32 s3, v31, 32
	s_add_i32 s10, s2, s3
	v_readlane_b32 s2, v31, 48
	s_add_i32 s10, s10, s2
	s_cmpk_lt_i32 s10, 0x100
	s_cbranch_scc0 .LBB0_506
	s_cmp_eq_u32 s7, 0
	v_sub_u32_e64 v31, s7, 1 clamp
	s_cselect_b64 s[2:3], -1, 0
	v_readfirstlane_b32 s9, v31
	s_cbranch_execz .LBB0_507

; DI int wave_isum(int v) {
;   v += __builtin_amdgcn_update_dpp(0, v, 0xB1, 0xf, 0xf, true);
;   v += __builtin_amdgcn_update_dpp(0, v, 0x4E, 0xf, 0xf, true);
;   v += __builtin_amdgcn_update_dpp(0, v, 0x141, 0xf, 0xf, true);
;   v += __builtin_amdgcn_update_dpp(0, v, 0x140, 0xf, 0xf, true);
;   return __builtin_amdgcn_readlane(v, 0) + __builtin_amdgcn_readlane(v, 16) + __builtin_amdgcn_readlane(v, 32) + __builtin_amdgcn_readlane(v, 48);
; }
; template <int NJ>
; DI void b1_select(const float* sc, int nj, unsigned* mo) {
;     ...
; #pragma unroll 1
;     ...
;       const unsigned cand = T | (1u << bit);
;       int c0 = 0, c1 = 0;
; #pragma unroll
;       for (int j = 0; j < NJ; ++j) { if (j & 1) c1 += (key[j] >= cand) ? 1 : 0; else c0 += (key[j] >= cand) ? 1 : 0; }
;       const int cnt = wave_isum(c0 + c1);
;       if (cnt >= 256) { T = cand; if (cnt == 256) break; }
;     }
.LBB0_510:
	s_lshl_b32 s0, 1, s6
	s_or_b32 s2, s97, s0
	v_cmp_le_u32_e32 vcc, s2, v2
	v_cmp_le_u32_e64 s[98:99], s2, v7
	v_cmp_le_u32_e64 s[100:101], s2, v3
	v_cndmask_b32_e64 v30, 0, 1, vcc
	v_cmp_le_u32_e32 vcc, s2, v9
	v_cndmask_b32_e64 v31, 0, 1, s[98:99]
	v_cmp_le_u32_e64 s[98:99], s2, v6
	v_cndmask_b32_e64 v32, 0, 1, s[100:101]
	v_cmp_le_u32_e64 s[100:101], s2, v13
	v_cndmask_b32_e64 v33, 0, 1, vcc
	v_cmp_le_u32_e32 vcc, s2, v10
	v_cndmask_b32_e64 v34, 0, 1, s[98:99]
	v_cmp_le_u32_e64 s[98:99], s2, v17
	v_cndmask_b32_e64 v35, 0, 1, s[100:101]
	v_cmp_le_u32_e64 s[100:101], s2, v14
	v_cndmask_b32_e64 v36, 0, 1, vcc
	v_cmp_le_u32_e32 vcc, s2, v21
	v_cndmask_b32_e64 v37, 0, 1, s[98:99]
	v_cmp_le_u32_e64 s[98:99], s2, v18
	v_cndmask_b32_e64 v38, 0, 1, s[100:101]
	v_cmp_le_u32_e64 s[100:101], s2, v25
	v_cndmask_b32_e64 v39, 0, 1, vcc
	v_cmp_le_u32_e32 vcc, s2, v22
	v_cndmask_b32_e64 v40, 0, 1, s[98:99]
	v_cmp_le_u32_e64 s[98:99], s2, v27
	v_cndmask_b32_e64 v41, 0, 1, s[100:101]
	v_cmp_le_u32_e64 s[100:101], s2, v5
	v_cndmask_b32_e64 v42, 0, 1, vcc
	v_cmp_le_u32_e32 vcc, s2, v11
	v_cndmask_b32_e64 v43, 0, 1, s[98:99]
	v_cmp_le_u32_e64 s[98:99], s2, v15
	v_addc_co_u32_e64 v31, s[100:101], 0, v31, s[100:101]
	v_cmp_le_u32_e64 s[100:101], s2, v19
	v_addc_co_u32_e32 v31, vcc, v31, v33, vcc
	v_cmp_le_u32_e32 vcc, s2, v23
	v_addc_co_u32_e64 v31, s[98:99], v31, v35, s[98:99]
	v_cmp_le_u32_e64 s[98:99], s2, v26
	v_addc_co_u32_e64 v31, s[100:101], v31, v37, s[100:101]
	v_cmp_le_u32_e64 s[100:101], s2, v28
	v_addc_co_u32_e32 v31, vcc, v31, v39, vcc
	v_cmp_le_u32_e32 vcc, s2, v29
	v_addc_co_u32_e64 v31, s[98:99], v31, v41, s[98:99]
	v_cmp_le_u32_e64 s[98:99], s2, v4
	v_addc_co_u32_e64 v31, s[100:101], v31, v43, s[100:101]
	v_cmp_le_u32_e64 s[100:101], s2, v8
	v_addc_co_u32_e32 v30, vcc, v31, v30, vcc
	v_cmp_le_u32_e32 vcc, s2, v12
	v_addc_co_u32_e64 v30, s[98:99], v30, v32, s[98:99]
	v_cmp_le_u32_e64 s[98:99], s2, v16
	v_addc_co_u32_e64 v30, s[100:101], v30, v34, s[100:101]
	v_cmp_le_u32_e64 s[100:101], s2, v20
	v_addc_co_u32_e32 v30, vcc, v30, v36, vcc
	v_cmp_le_u32_e32 vcc, s2, v24
	v_addc_co_u32_e64 v30, s[98:99], v30, v38, s[98:99]
	v_addc_co_u32_e64 v30, s[100:101], v30, v40, s[100:101]
	v_addc_co_u32_e32 v30, vcc, v30, v42, vcc
	s_nop 1
	v_add_u32_dpp v30, v30, v30 quad_perm:[1,0,3,2] row_mask:0xf bank_mask:0xf bound_ctrl:1
	s_nop 1
	v_add_u32_dpp v30, v30, v30 quad_perm:[2,3,0,1] row_mask:0xf bank_mask:0xf bound_ctrl:1
	s_nop 1
	v_add_u32_dpp v30, v30, v30 row_half_mirror row_mask:0xf bank_mask:0xf bound_ctrl:1
	s_nop 1
	v_add_u32_dpp v30, v30, v30 row_mirror row_mask:0xf bank_mask:0xf bound_ctrl:1
	s_nop 0
	v_readlane_b32 s0, v30, 0
	v_readlane_b32 s1, v30, 16
	v_readlane_b32 s3, v30, 32
	s_add_i32 s0, s1, s0
	v_readlane_b32 s4, v30, 48
	s_add_i32 s0, s0, s3
	s_add_i32 s3, s0, s4
	s_cmpk_lg_i32 s3, 0x100
	s_cselect_b64 s[0:1], -1, 0
	s_cmpk_gt_i32 s3, 0xff
	s_cselect_b32 s97, s2, s97
	s_add_i32 s2, s6, -1
	s_cmp_gt_i32 s6, 0
	s_mov_b32 s6, s2
	s_cselect_b64 s[2:3], -1, 0
	s_and_b64 s[0:1], s[0:1], s[2:3]
	s_and_b64 vcc, exec, s[0:1]
	s_cbranch_vccnz .LBB0_510

; DI int wave_isum(int v) {
;   v += __builtin_amdgcn_update_dpp(0, v, 0xB1, 0xf, 0xf, true);
;   v += __builtin_amdgcn_update_dpp(0, v, 0x4E, 0xf, 0xf, true);
;   v += __builtin_amdgcn_update_dpp(0, v, 0x141, 0xf, 0xf, true);
;   v += __builtin_amdgcn_update_dpp(0, v, 0x140, 0xf, 0xf, true);
;   return __builtin_amdgcn_readlane(v, 0) + __builtin_amdgcn_readlane(v, 16) + __builtin_amdgcn_readlane(v, 32) + __builtin_amdgcn_readlane(v, 48);
; template <int NJ>
; DI void b1_select(const float* sc, int nj, unsigned* mo) {
;     ...
;     unsigned E = M >> 23;
; #pragma unroll 1
;     for (int i = 0; i < 8; ++i) {
;       const unsigned cand = E << 23;
;       int c0 = 0, c1 = 0;
; #pragma unroll
;       for (int j = 0; j < NJ; ++j) { if (j & 1) c1 += (key[j] >= cand) ? 1 : 0; else c0 += (key[j] >= cand) ? 1 : 0; }
;       const int cnt = wave_isum(c0 + c1);
;       if (cnt >= 256) { T = cand; bit = 22; exact = (cnt == 256); break; }
;       if (E == 0u) break;
;       --E;
;     }
.LBB0_568:
	s_lshl_b32 s8, s7, 23
	v_cmp_le_u32_e32 vcc, s8, v2
	s_mov_b64 s[4:5], -1
	s_nop 0
	v_cndmask_b32_e64 v31, 0, 1, vcc
	v_cmp_le_u32_e32 vcc, s8, v7
	v_cmp_le_u32_e64 s[98:99], s8, v3
	v_cmp_le_u32_e64 s[100:101], s8, v9
	v_cndmask_b32_e64 v32, 0, 1, vcc
	v_cmp_le_u32_e32 vcc, s8, v6
	v_cndmask_b32_e64 v33, 0, 1, s[98:99]
	v_cmp_le_u32_e64 s[98:99], s8, v13
	v_cndmask_b32_e64 v34, 0, 1, s[100:101]
	v_cmp_le_u32_e64 s[100:101], s8, v10
	v_cndmask_b32_e64 v35, 0, 1, vcc
	v_cmp_le_u32_e32 vcc, s8, v17
	v_cndmask_b32_e64 v36, 0, 1, s[98:99]
	v_cmp_le_u32_e64 s[98:99], s8, v14
	v_cndmask_b32_e64 v37, 0, 1, s[100:101]
	v_cmp_le_u32_e64 s[100:101], s8, v21
	v_cndmask_b32_e64 v38, 0, 1, vcc
	v_cmp_le_u32_e32 vcc, s8, v18
	v_cndmask_b32_e64 v39, 0, 1, s[98:99]
	v_cmp_le_u32_e64 s[98:99], s8, v25
	v_cndmask_b32_e64 v40, 0, 1, s[100:101]
	v_cmp_le_u32_e64 s[100:101], s8, v22
	v_cndmask_b32_e64 v41, 0, 1, vcc
	v_cmp_le_u32_e32 vcc, s8, v28
	v_cndmask_b32_e64 v42, 0, 1, s[98:99]
	v_cmp_le_u32_e64 s[98:99], s8, v5
	v_cndmask_b32_e64 v43, 0, 1, s[100:101]
	v_cmp_le_u32_e64 s[100:101], s8, v11
	v_cndmask_b32_e64 v44, 0, 1, vcc
	v_cmp_le_u32_e32 vcc, s8, v15
	v_addc_co_u32_e64 v32, s[98:99], 0, v32, s[98:99]
	v_cmp_le_u32_e64 s[98:99], s8, v19
	v_addc_co_u32_e64 v32, s[100:101], v32, v34, s[100:101]
	v_cmp_le_u32_e64 s[100:101], s8, v23
	v_addc_co_u32_e32 v32, vcc, v32, v36, vcc
	v_cmp_le_u32_e32 vcc, s8, v26
	v_addc_co_u32_e64 v32, s[98:99], v32, v38, s[98:99]
	v_cmp_le_u32_e64 s[98:99], s8, v27
	v_addc_co_u32_e64 v32, s[100:101], v32, v40, s[100:101]
	v_cmp_le_u32_e64 s[100:101], s8, v29
	v_addc_co_u32_e32 v32, vcc, v32, v42, vcc
	v_cmp_le_u32_e32 vcc, s8, v4
	v_addc_co_u32_e64 v32, s[98:99], v32, v44, s[98:99]
	v_cmp_le_u32_e64 s[98:99], s8, v8
	v_addc_co_u32_e64 v31, s[100:101], v32, v31, s[100:101]
	v_cmp_le_u32_e64 s[100:101], s8, v12
	v_addc_co_u32_e32 v31, vcc, v31, v33, vcc
	v_cmp_le_u32_e32 vcc, s8, v16
	v_addc_co_u32_e64 v31, s[98:99], v31, v35, s[98:99]
	v_cmp_le_u32_e64 s[98:99], s8, v20
	v_addc_co_u32_e64 v31, s[100:101], v31, v37, s[100:101]
	v_cmp_le_u32_e64 s[100:101], s8, v24
	v_addc_co_u32_e32 v31, vcc, v31, v39, vcc
	v_addc_co_u32_e64 v31, s[98:99], v31, v41, s[98:99]
	v_addc_co_u32_e64 v31, s[100:101], v31, v43, s[100:101]
	s_nop 1
	v_add_u32_dpp v31, v31, v31 quad_perm:[1,0,3,2] row_mask:0xf bank_mask:0xf bound_ctrl:1
	s_nop 1
	v_add_u32_dpp v31, v31, v31 quad_perm:[2,3,0,1] row_mask:0xf bank_mask:0xf bound_ctrl:1
	s_nop 1
	v_add_u32_dpp v31, v31, v31 row_half_mirror row_mask:0xf bank_mask:0xf bound_ctrl:1
	s_nop 1
	v_add_u32_dpp v31, v31, v31 row_mirror row_mask:0xf bank_mask:0xf bound_ctrl:1
	s_nop 0
	v_readlane_b32 s2, v31, 0
	v_readlane_b32 s3, v31, 16
	s_add_i32 s2, s3, s2
	v_readlane_b32 s3, v31, 32
	s_add_i32 s10, s2, s3
	v_readlane_b32 s2, v31, 48
	s_add_i32 s10, s10, s2
	s_cmpk_lt_i32 s10, 0x100
	s_cbranch_scc0 .LBB0_571
	s_cmp_eq_u32 s7, 0
	v_sub_u32_e64 v31, s7, 1 clamp
	s_cselect_b64 s[2:3], -1, 0
	v_readfirstlane_b32 s9, v31
	s_cbranch_execz .LBB0_572

; DI int wave_isum(int v) {
;   v += __builtin_amdgcn_update_dpp(0, v, 0xB1, 0xf, 0xf, true);
;   v += __builtin_amdgcn_update_dpp(0, v, 0x4E, 0xf, 0xf, true);
;   v += __builtin_amdgcn_update_dpp(0, v, 0x141, 0xf, 0xf, true);
;   v += __builtin_amdgcn_update_dpp(0, v, 0x140, 0xf, 0xf, true);
;   return __builtin_amdgcn_readlane(v, 0) + __builtin_amdgcn_readlane(v, 16) + __builtin_amdgcn_readlane(v, 32) + __builtin_amdgcn_readlane(v, 48);
; template <int NJ>
; DI void b1_select(const float* sc, int nj, unsigned* mo) {
;     ...
; #pragma unroll 1
;     ...
;       const unsigned cand = T | (1u << bit);
;       int c0 = 0, c1 = 0;
; #pragma unroll
;       for (int j = 0; j < NJ; ++j) { if (j & 1) c1 += (key[j] >= cand) ? 1 : 0; else c0 += (key[j] >= cand) ? 1 : 0; }
;       const int cnt = wave_isum(c0 + c1);
;       if (cnt >= 256) { T = cand; if (cnt == 256) break; }
;     }
.LBB0_575:
	s_lshl_b32 s0, 1, s6
	s_or_b32 s2, s60, s0
	v_cmp_le_u32_e32 vcc, s2, v2
	v_cmp_le_u32_e64 s[98:99], s2, v7
	v_cmp_le_u32_e64 s[100:101], s2, v3
	v_cndmask_b32_e64 v30, 0, 1, vcc
	v_cmp_le_u32_e32 vcc, s2, v9
	v_cndmask_b32_e64 v31, 0, 1, s[98:99]
	v_cmp_le_u32_e64 s[98:99], s2, v6
	v_cndmask_b32_e64 v32, 0, 1, s[100:101]
	v_cmp_le_u32_e64 s[100:101], s2, v13
	v_cndmask_b32_e64 v33, 0, 1, vcc
	v_cmp_le_u32_e32 vcc, s2, v10
	v_cndmask_b32_e64 v34, 0, 1, s[98:99]
	v_cmp_le_u32_e64 s[98:99], s2, v17
	v_cndmask_b32_e64 v35, 0, 1, s[100:101]
	v_cmp_le_u32_e64 s[100:101], s2, v14
	v_cndmask_b32_e64 v36, 0, 1, vcc
	v_cmp_le_u32_e32 vcc, s2, v21
	v_cndmask_b32_e64 v37, 0, 1, s[98:99]
	v_cmp_le_u32_e64 s[98:99], s2, v18
	v_cndmask_b32_e64 v38, 0, 1, s[100:101]
	v_cmp_le_u32_e64 s[100:101], s2, v25
	v_cndmask_b32_e64 v39, 0, 1, vcc
	v_cmp_le_u32_e32 vcc, s2, v22
	v_cndmask_b32_e64 v40, 0, 1, s[98:99]
	v_cmp_le_u32_e64 s[98:99], s2, v28
	v_cndmask_b32_e64 v41, 0, 1, s[100:101]
	v_cmp_le_u32_e64 s[100:101], s2, v5
	v_cndmask_b32_e64 v42, 0, 1, vcc
	v_cmp_le_u32_e32 vcc, s2, v11
	v_cndmask_b32_e64 v43, 0, 1, s[98:99]
	v_cmp_le_u32_e64 s[98:99], s2, v15
	v_addc_co_u32_e64 v31, s[100:101], 0, v31, s[100:101]
	v_cmp_le_u32_e64 s[100:101], s2, v19
	v_addc_co_u32_e32 v31, vcc, v31, v33, vcc
	v_cmp_le_u32_e32 vcc, s2, v23
	v_addc_co_u32_e64 v31, s[98:99], v31, v35, s[98:99]
	v_cmp_le_u32_e64 s[98:99], s2, v26
	v_addc_co_u32_e64 v31, s[100:101], v31, v37, s[100:101]
	v_cmp_le_u32_e64 s[100:101], s2, v27
	v_addc_co_u32_e32 v31, vcc, v31, v39, vcc
	v_cmp_le_u32_e32 vcc, s2, v29
	v_addc_co_u32_e64 v31, s[98:99], v31, v41, s[98:99]
	v_cmp_le_u32_e64 s[98:99], s2, v4
	v_addc_co_u32_e64 v31, s[100:101], v31, v43, s[100:101]
	v_cmp_le_u32_e64 s[100:101], s2, v8
	v_addc_co_u32_e32 v30, vcc, v31, v30, vcc
	v_cmp_le_u32_e32 vcc, s2, v12
	v_addc_co_u32_e64 v30, s[98:99], v30, v32, s[98:99]
	v_cmp_le_u32_e64 s[98:99], s2, v16
	v_addc_co_u32_e64 v30, s[100:101], v30, v34, s[100:101]
	v_cmp_le_u32_e64 s[100:101], s2, v20
	v_addc_co_u32_e32 v30, vcc, v30, v36, vcc
	v_cmp_le_u32_e32 vcc, s2, v24
	v_addc_co_u32_e64 v30, s[98:99], v30, v38, s[98:99]
	v_addc_co_u32_e64 v30, s[100:101], v30, v40, s[100:101]
	v_addc_co_u32_e32 v30, vcc, v30, v42, vcc
	s_nop 1
	v_add_u32_dpp v30, v30, v30 quad_perm:[1,0,3,2] row_mask:0xf bank_mask:0xf bound_ctrl:1
	s_nop 1
	v_add_u32_dpp v30, v30, v30 quad_perm:[2,3,0,1] row_mask:0xf bank_mask:0xf bound_ctrl:1
	s_nop 1
	v_add_u32_dpp v30, v30, v30 row_half_mirror row_mask:0xf bank_mask:0xf bound_ctrl:1
	s_nop 1
	v_add_u32_dpp v30, v30, v30 row_mirror row_mask:0xf bank_mask:0xf bound_ctrl:1
	s_nop 0
	v_readlane_b32 s0, v30, 0
	v_readlane_b32 s1, v30, 16
	v_readlane_b32 s3, v30, 32
	s_add_i32 s0, s1, s0
	v_readlane_b32 s4, v30, 48
	s_add_i32 s0, s0, s3
	s_add_i32 s3, s0, s4
	s_cmpk_lg_i32 s3, 0x100
	s_cselect_b64 s[0:1], -1, 0
	s_cmpk_gt_i32 s3, 0xff
	s_cselect_b32 s60, s2, s60
	s_add_i32 s2, s6, -1
	s_cmp_gt_i32 s6, 0
	s_mov_b32 s6, s2
	s_cselect_b64 s[2:3], -1, 0
	s_and_b64 s[0:1], s[0:1], s[2:3]
	s_and_b64 vcc, exec, s[0:1]
	s_cbranch_vccnz .LBB0_575

; DI int wave_isum(int v) {
;   v += __builtin_amdgcn_update_dpp(0, v, 0xB1, 0xf, 0xf, true);
;   v += __builtin_amdgcn_update_dpp(0, v, 0x4E, 0xf, 0xf, true);
;   v += __builtin_amdgcn_update_dpp(0, v, 0x141, 0xf, 0xf, true);
;   v += __builtin_amdgcn_update_dpp(0, v, 0x140, 0xf, 0xf, true);
;   return __builtin_amdgcn_readlane(v, 0) + __builtin_amdgcn_readlane(v, 16) + __builtin_amdgcn_readlane(v, 32) + __builtin_amdgcn_readlane(v, 48);
; template <int NJ>
; DI void b1_select(const float* sc, int nj, unsigned* mo) {
;     ...
;     unsigned E = M >> 23;
; #pragma unroll 1
;     for (int i = 0; i < 8; ++i) {
;       const unsigned cand = E << 23;
;       int c0 = 0, c1 = 0;
; #pragma unroll
;       for (int j = 0; j < NJ; ++j) { if (j & 1) c1 += (key[j] >= cand) ? 1 : 0; else c0 += (key[j] >= cand) ? 1 : 0; }
;       const int cnt = wave_isum(c0 + c1);
;       if (cnt >= 256) { T = cand; bit = 22; exact = (cnt == 256); break; }
;       if (E == 0u) break;
;       --E;
;     }
.LBB0_628:
	s_lshl_b32 s8, s7, 23
	v_cmp_le_u32_e32 vcc, s8, v2
	s_mov_b64 s[4:5], -1
	s_nop 0
	v_cndmask_b32_e64 v27, 0, 1, vcc
	v_cmp_le_u32_e32 vcc, s8, v7
	v_cmp_le_u32_e64 s[98:99], s8, v3
	v_cmp_le_u32_e64 s[100:101], s8, v9
	v_cndmask_b32_e64 v28, 0, 1, vcc
	v_cmp_le_u32_e32 vcc, s8, v6
	v_cndmask_b32_e64 v29, 0, 1, s[98:99]
	v_cmp_le_u32_e64 s[98:99], s8, v13
	v_cndmask_b32_e64 v30, 0, 1, s[100:101]
	v_cmp_le_u32_e64 s[100:101], s8, v10
	v_cndmask_b32_e64 v31, 0, 1, vcc
	v_cmp_le_u32_e32 vcc, s8, v17
	v_cndmask_b32_e64 v32, 0, 1, s[98:99]
	v_cmp_le_u32_e64 s[98:99], s8, v14
	v_cndmask_b32_e64 v33, 0, 1, s[100:101]
	v_cmp_le_u32_e64 s[100:101], s8, v21
	v_cndmask_b32_e64 v34, 0, 1, vcc
	v_cmp_le_u32_e32 vcc, s8, v18
	v_cndmask_b32_e64 v35, 0, 1, s[98:99]
	v_cmp_le_u32_e64 s[98:99], s8, v23
	v_cndmask_b32_e64 v36, 0, 1, s[100:101]
	v_cmp_le_u32_e64 s[100:101], s8, v5
	v_cndmask_b32_e64 v37, 0, 1, vcc
	v_cmp_le_u32_e32 vcc, s8, v11
	v_cndmask_b32_e64 v38, 0, 1, s[98:99]
	v_cmp_le_u32_e64 s[98:99], s8, v15
	v_addc_co_u32_e64 v28, s[100:101], 0, v28, s[100:101]
	v_cmp_le_u32_e64 s[100:101], s8, v19
	v_addc_co_u32_e32 v28, vcc, v28, v30, vcc
	v_cmp_le_u32_e32 vcc, s8, v22
	v_addc_co_u32_e64 v28, s[98:99], v28, v32, s[98:99]
	v_cmp_le_u32_e64 s[98:99], s8, v24
	v_addc_co_u32_e64 v28, s[100:101], v28, v34, s[100:101]
	v_cmp_le_u32_e64 s[100:101], s8, v25
	v_addc_co_u32_e32 v28, vcc, v28, v36, vcc
	v_cmp_le_u32_e32 vcc, s8, v4
	v_addc_co_u32_e64 v28, s[98:99], v28, v38, s[98:99]
	v_cmp_le_u32_e64 s[98:99], s8, v8
	v_addc_co_u32_e64 v27, s[100:101], v28, v27, s[100:101]
	v_cmp_le_u32_e64 s[100:101], s8, v12
	v_addc_co_u32_e32 v27, vcc, v27, v29, vcc
	v_cmp_le_u32_e32 vcc, s8, v16
	v_addc_co_u32_e64 v27, s[98:99], v27, v31, s[98:99]
	v_cmp_le_u32_e64 s[98:99], s8, v20
	v_addc_co_u32_e64 v27, s[100:101], v27, v33, s[100:101]
	v_addc_co_u32_e32 v27, vcc, v27, v35, vcc
	v_addc_co_u32_e64 v27, s[98:99], v27, v37, s[98:99]
	s_nop 1
	v_add_u32_dpp v27, v27, v27 quad_perm:[1,0,3,2] row_mask:0xf bank_mask:0xf bound_ctrl:1
	s_nop 1
	v_add_u32_dpp v27, v27, v27 quad_perm:[2,3,0,1] row_mask:0xf bank_mask:0xf bound_ctrl:1
	s_nop 1
	v_add_u32_dpp v27, v27, v27 row_half_mirror row_mask:0xf bank_mask:0xf bound_ctrl:1
	s_nop 1
	v_add_u32_dpp v27, v27, v27 row_mirror row_mask:0xf bank_mask:0xf bound_ctrl:1
	s_nop 0
	v_readlane_b32 s2, v27, 0
	v_readlane_b32 s3, v27, 16
	s_add_i32 s2, s3, s2
	v_readlane_b32 s3, v27, 32
	s_add_i32 s10, s2, s3
	v_readlane_b32 s2, v27, 48
	s_add_i32 s10, s10, s2
	s_cmpk_lt_i32 s10, 0x100
	s_cbranch_scc0 .LBB0_631
	s_cmp_eq_u32 s7, 0
	v_sub_u32_e64 v27, s7, 1 clamp
	s_cselect_b64 s[2:3], -1, 0
	v_readfirstlane_b32 s9, v27
	s_cbranch_execz .LBB0_632

; DI int wave_isum(int v) {
;   v += __builtin_amdgcn_update_dpp(0, v, 0xB1, 0xf, 0xf, true);
;   v += __builtin_amdgcn_update_dpp(0, v, 0x4E, 0xf, 0xf, true);
;   v += __builtin_amdgcn_update_dpp(0, v, 0x141, 0xf, 0xf, true);
;   v += __builtin_amdgcn_update_dpp(0, v, 0x140, 0xf, 0xf, true);
;   return __builtin_amdgcn_readlane(v, 0) + __builtin_amdgcn_readlane(v, 16) + __builtin_amdgcn_readlane(v, 32) + __builtin_amdgcn_readlane(v, 48);
; template <int NJ>
; DI void b1_select(const float* sc, int nj, unsigned* mo) {
;     ...
; #pragma unroll 1
;     ...
;       const unsigned cand = T | (1u << bit);
;       int c0 = 0, c1 = 0;
; #pragma unroll
;       for (int j = 0; j < NJ; ++j) { if (j & 1) c1 += (key[j] >= cand) ? 1 : 0; else c0 += (key[j] >= cand) ? 1 : 0; }
;       const int cnt = wave_isum(c0 + c1);
;       if (cnt >= 256) { T = cand; if (cnt == 256) break; }
;     }
.LBB0_635:
	s_lshl_b32 s0, 1, s6
	s_or_b32 s2, s94, s0
	v_cmp_le_u32_e32 vcc, s2, v2
	v_cmp_le_u32_e64 s[98:99], s2, v7
	v_cmp_le_u32_e64 s[100:101], s2, v3
	v_cndmask_b32_e64 v26, 0, 1, vcc
	v_cmp_le_u32_e32 vcc, s2, v9
	v_cndmask_b32_e64 v27, 0, 1, s[98:99]
	v_cmp_le_u32_e64 s[98:99], s2, v6
	v_cndmask_b32_e64 v28, 0, 1, s[100:101]
	v_cmp_le_u32_e64 s[100:101], s2, v13
	v_cndmask_b32_e64 v29, 0, 1, vcc
	v_cmp_le_u32_e32 vcc, s2, v10
	v_cndmask_b32_e64 v30, 0, 1, s[98:99]
	v_cmp_le_u32_e64 s[98:99], s2, v17
	v_cndmask_b32_e64 v31, 0, 1, s[100:101]
	v_cmp_le_u32_e64 s[100:101], s2, v14
	v_cndmask_b32_e64 v32, 0, 1, vcc
	v_cmp_le_u32_e32 vcc, s2, v21
	v_cndmask_b32_e64 v33, 0, 1, s[98:99]
	v_cmp_le_u32_e64 s[98:99], s2, v18
	v_cndmask_b32_e64 v34, 0, 1, s[100:101]
	v_cmp_le_u32_e64 s[100:101], s2, v23
	v_cndmask_b32_e64 v35, 0, 1, vcc
	v_cmp_le_u32_e32 vcc, s2, v5
	v_cndmask_b32_e64 v36, 0, 1, s[98:99]
	v_cmp_le_u32_e64 s[98:99], s2, v11
	v_cndmask_b32_e64 v37, 0, 1, s[100:101]
	v_cmp_le_u32_e64 s[100:101], s2, v15
	v_addc_co_u32_e32 v27, vcc, 0, v27, vcc
	v_cmp_le_u32_e32 vcc, s2, v19
	v_addc_co_u32_e64 v27, s[98:99], v27, v29, s[98:99]
	v_cmp_le_u32_e64 s[98:99], s2, v22
	v_addc_co_u32_e64 v27, s[100:101], v27, v31, s[100:101]
	v_cmp_le_u32_e64 s[100:101], s2, v24
	v_addc_co_u32_e32 v27, vcc, v27, v33, vcc
	v_cmp_le_u32_e32 vcc, s2, v25
	v_addc_co_u32_e64 v27, s[98:99], v27, v35, s[98:99]
	v_cmp_le_u32_e64 s[98:99], s2, v4
	v_addc_co_u32_e64 v27, s[100:101], v27, v37, s[100:101]
	v_cmp_le_u32_e64 s[100:101], s2, v8
	v_addc_co_u32_e32 v26, vcc, v27, v26, vcc
	v_cmp_le_u32_e32 vcc, s2, v12
	v_addc_co_u32_e64 v26, s[98:99], v26, v28, s[98:99]
	v_cmp_le_u32_e64 s[98:99], s2, v16
	v_addc_co_u32_e64 v26, s[100:101], v26, v30, s[100:101]
	v_cmp_le_u32_e64 s[100:101], s2, v20
	v_addc_co_u32_e32 v26, vcc, v26, v32, vcc
	v_addc_co_u32_e64 v26, s[98:99], v26, v34, s[98:99]
	v_addc_co_u32_e64 v26, s[100:101], v26, v36, s[100:101]
	s_nop 1
	v_add_u32_dpp v26, v26, v26 quad_perm:[1,0,3,2] row_mask:0xf bank_mask:0xf bound_ctrl:1
	s_nop 1
	v_add_u32_dpp v26, v26, v26 quad_perm:[2,3,0,1] row_mask:0xf bank_mask:0xf bound_ctrl:1
	s_nop 1
	v_add_u32_dpp v26, v26, v26 row_half_mirror row_mask:0xf bank_mask:0xf bound_ctrl:1
	s_nop 1
	v_add_u32_dpp v26, v26, v26 row_mirror row_mask:0xf bank_mask:0xf bound_ctrl:1
	s_nop 0
	v_readlane_b32 s0, v26, 0
	v_readlane_b32 s1, v26, 16
	v_readlane_b32 s3, v26, 32
	s_add_i32 s0, s1, s0
	v_readlane_b32 s4, v26, 48
	s_add_i32 s0, s0, s3
	s_add_i32 s3, s0, s4
	s_cmpk_lg_i32 s3, 0x100
	s_cselect_b64 s[0:1], -1, 0
	s_cmpk_gt_i32 s3, 0xff
	s_cselect_b32 s94, s2, s94
	s_add_i32 s2, s6, -1
	s_cmp_gt_i32 s6, 0
	s_mov_b32 s6, s2
	s_cselect_b64 s[2:3], -1, 0
	s_and_b64 s[0:1], s[0:1], s[2:3]
	s_and_b64 vcc, exec, s[0:1]
	s_cbranch_vccnz .LBB0_635

; DI int wave_isum(int v) {
;   v += __builtin_amdgcn_update_dpp(0, v, 0xB1, 0xf, 0xf, true);
;   v += __builtin_amdgcn_update_dpp(0, v, 0x4E, 0xf, 0xf, true);
;   v += __builtin_amdgcn_update_dpp(0, v, 0x141, 0xf, 0xf, true);
;   v += __builtin_amdgcn_update_dpp(0, v, 0x140, 0xf, 0xf, true);
;   return __builtin_amdgcn_readlane(v, 0) + __builtin_amdgcn_readlane(v, 16) + __builtin_amdgcn_readlane(v, 32) + __builtin_amdgcn_readlane(v, 48);
; template <int NJ>
; DI void b1_select(const float* sc, int nj, unsigned* mo) {
;     ...
;     unsigned E = M >> 23;
; #pragma unroll 1
;     for (int i = 0; i < 8; ++i) {
;       const unsigned cand = E << 23;
;       int c0 = 0, c1 = 0;
; #pragma unroll
;       for (int j = 0; j < NJ; ++j) { if (j & 1) c1 += (key[j] >= cand) ? 1 : 0; else c0 += (key[j] >= cand) ? 1 : 0; }
;       const int cnt = wave_isum(c0 + c1);
;       if (cnt >= 256) { T = cand; bit = 22; exact = (cnt == 256); break; }
;       if (E == 0u) break;
;       --E;
;     }
.LBB0_683:
	s_lshl_b32 s8, s7, 23
	v_cmp_le_u32_e32 vcc, s8, v2
	s_mov_b64 s[4:5], -1
	s_nop 0
	v_cndmask_b32_e64 v27, 0, 1, vcc
	v_cmp_le_u32_e32 vcc, s8, v7
	v_cmp_le_u32_e64 s[98:99], s8, v4
	v_cmp_le_u32_e64 s[100:101], s8, v9
	v_cndmask_b32_e64 v28, 0, 1, vcc
	v_cmp_le_u32_e32 vcc, s8, v6
	v_cndmask_b32_e64 v29, 0, 1, s[98:99]
	v_cmp_le_u32_e64 s[98:99], s8, v13
	v_cndmask_b32_e64 v30, 0, 1, s[100:101]
	v_cmp_le_u32_e64 s[100:101], s8, v10
	v_cndmask_b32_e64 v31, 0, 1, vcc
	v_cmp_le_u32_e32 vcc, s8, v17
	v_cndmask_b32_e64 v32, 0, 1, s[98:99]
	v_cmp_le_u32_e64 s[98:99], s8, v14
	v_cndmask_b32_e64 v33, 0, 1, s[100:101]
	v_cmp_le_u32_e64 s[100:101], s8, v21
	v_cndmask_b32_e64 v34, 0, 1, vcc
	v_cmp_le_u32_e32 vcc, s8, v18
	v_cndmask_b32_e64 v35, 0, 1, s[98:99]
	v_cmp_le_u32_e64 s[98:99], s8, v23
	v_cndmask_b32_e64 v36, 0, 1, s[100:101]
	v_cmp_le_u32_e64 s[100:101], s8, v3
	v_cndmask_b32_e64 v37, 0, 1, vcc
	v_cmp_le_u32_e32 vcc, s8, v11
	v_cndmask_b32_e64 v38, 0, 1, s[98:99]
	v_cmp_le_u32_e64 s[98:99], s8, v15
	v_addc_co_u32_e64 v28, s[100:101], 0, v28, s[100:101]
	v_cmp_le_u32_e64 s[100:101], s8, v19
	v_addc_co_u32_e32 v28, vcc, v28, v30, vcc
	v_cmp_le_u32_e32 vcc, s8, v22
	v_addc_co_u32_e64 v28, s[98:99], v28, v32, s[98:99]
	v_cmp_le_u32_e64 s[98:99], s8, v24
	v_addc_co_u32_e64 v28, s[100:101], v28, v34, s[100:101]
	v_cmp_le_u32_e64 s[100:101], s8, v25
	v_addc_co_u32_e32 v28, vcc, v28, v36, vcc
	v_cmp_le_u32_e32 vcc, s8, v5
	v_addc_co_u32_e64 v28, s[98:99], v28, v38, s[98:99]
	v_cmp_le_u32_e64 s[98:99], s8, v8
	v_addc_co_u32_e64 v27, s[100:101], v28, v27, s[100:101]
	v_cmp_le_u32_e64 s[100:101], s8, v12
	v_addc_co_u32_e32 v27, vcc, v27, v29, vcc
	v_cmp_le_u32_e32 vcc, s8, v16
	v_addc_co_u32_e64 v27, s[98:99], v27, v31, s[98:99]
	v_cmp_le_u32_e64 s[98:99], s8, v20
	v_addc_co_u32_e64 v27, s[100:101], v27, v33, s[100:101]
	v_addc_co_u32_e32 v27, vcc, v27, v35, vcc
	v_addc_co_u32_e64 v27, s[98:99], v27, v37, s[98:99]
	s_nop 1
	v_add_u32_dpp v27, v27, v27 quad_perm:[1,0,3,2] row_mask:0xf bank_mask:0xf bound_ctrl:1
	s_nop 1
	v_add_u32_dpp v27, v27, v27 quad_perm:[2,3,0,1] row_mask:0xf bank_mask:0xf bound_ctrl:1
	s_nop 1
	v_add_u32_dpp v27, v27, v27 row_half_mirror row_mask:0xf bank_mask:0xf bound_ctrl:1
	s_nop 1
	v_add_u32_dpp v27, v27, v27 row_mirror row_mask:0xf bank_mask:0xf bound_ctrl:1
	s_nop 0
	v_readlane_b32 s2, v27, 0
	v_readlane_b32 s3, v27, 16
	s_add_i32 s2, s3, s2
	v_readlane_b32 s3, v27, 32
	s_add_i32 s10, s2, s3
	v_readlane_b32 s2, v27, 48
	s_add_i32 s10, s10, s2
	s_cmpk_lt_i32 s10, 0x100
	s_cbranch_scc0 .LBB0_686
	s_cmp_eq_u32 s7, 0
	v_sub_u32_e64 v27, s7, 1 clamp
	s_cselect_b64 s[2:3], -1, 0
	v_readfirstlane_b32 s9, v27
	s_cbranch_execz .LBB0_687

; DI int wave_isum(int v) {
;   v += __builtin_amdgcn_update_dpp(0, v, 0xB1, 0xf, 0xf, true);
;   v += __builtin_amdgcn_update_dpp(0, v, 0x4E, 0xf, 0xf, true);
;   v += __builtin_amdgcn_update_dpp(0, v, 0x141, 0xf, 0xf, true);
;   v += __builtin_amdgcn_update_dpp(0, v, 0x140, 0xf, 0xf, true);
;   return __builtin_amdgcn_readlane(v, 0) + __builtin_amdgcn_readlane(v, 16) + __builtin_amdgcn_readlane(v, 32) + __builtin_amdgcn_readlane(v, 48);
; template <int NJ>
; DI void b1_select(const float* sc, int nj, unsigned* mo) {
;     ...
; #pragma unroll 1
;     ...
;       const unsigned cand = T | (1u << bit);
;       int c0 = 0, c1 = 0;
; #pragma unroll
;       for (int j = 0; j < NJ; ++j) { if (j & 1) c1 += (key[j] >= cand) ? 1 : 0; else c0 += (key[j] >= cand) ? 1 : 0; }
;       const int cnt = wave_isum(c0 + c1);
;       if (cnt >= 256) { T = cand; if (cnt == 256) break; }
;     }
.LBB0_692:
	s_lshl_b32 s0, 1, s6
	s_or_b32 s2, s52, s0
	v_cmp_le_u32_e32 vcc, s2, v2
	v_cmp_le_u32_e64 s[98:99], s2, v7
	v_cmp_le_u32_e64 s[100:101], s2, v4
	v_cndmask_b32_e64 v26, 0, 1, vcc
	v_cmp_le_u32_e32 vcc, s2, v9
	v_cndmask_b32_e64 v27, 0, 1, s[98:99]
	v_cmp_le_u32_e64 s[98:99], s2, v6
	v_cndmask_b32_e64 v28, 0, 1, s[100:101]
	v_cmp_le_u32_e64 s[100:101], s2, v13
	v_cndmask_b32_e64 v29, 0, 1, vcc
	v_cmp_le_u32_e32 vcc, s2, v10
	v_cndmask_b32_e64 v30, 0, 1, s[98:99]
	v_cmp_le_u32_e64 s[98:99], s2, v17
	v_cndmask_b32_e64 v31, 0, 1, s[100:101]
	v_cmp_le_u32_e64 s[100:101], s2, v14
	v_cndmask_b32_e64 v32, 0, 1, vcc
	v_cmp_le_u32_e32 vcc, s2, v21
	v_cndmask_b32_e64 v33, 0, 1, s[98:99]
	v_cmp_le_u32_e64 s[98:99], s2, v18
	v_cndmask_b32_e64 v34, 0, 1, s[100:101]
	v_cmp_le_u32_e64 s[100:101], s2, v23
	v_cndmask_b32_e64 v35, 0, 1, vcc
	v_cmp_le_u32_e32 vcc, s2, v3
	v_cndmask_b32_e64 v36, 0, 1, s[98:99]
	v_cmp_le_u32_e64 s[98:99], s2, v11
	v_cndmask_b32_e64 v37, 0, 1, s[100:101]
	v_cmp_le_u32_e64 s[100:101], s2, v15
	v_addc_co_u32_e32 v27, vcc, 0, v27, vcc
	v_cmp_le_u32_e32 vcc, s2, v19
	v_addc_co_u32_e64 v27, s[98:99], v27, v29, s[98:99]
	v_cmp_le_u32_e64 s[98:99], s2, v22
	v_addc_co_u32_e64 v27, s[100:101], v27, v31, s[100:101]
	v_cmp_le_u32_e64 s[100:101], s2, v24
	v_addc_co_u32_e32 v27, vcc, v27, v33, vcc
	v_cmp_le_u32_e32 vcc, s2, v25
	v_addc_co_u32_e64 v27, s[98:99], v27, v35, s[98:99]
	v_cmp_le_u32_e64 s[98:99], s2, v5
	v_addc_co_u32_e64 v27, s[100:101], v27, v37, s[100:101]
	v_cmp_le_u32_e64 s[100:101], s2, v8
	v_addc_co_u32_e32 v26, vcc, v27, v26, vcc
	v_cmp_le_u32_e32 vcc, s2, v12
	v_addc_co_u32_e64 v26, s[98:99], v26, v28, s[98:99]
	v_cmp_le_u32_e64 s[98:99], s2, v16
	v_addc_co_u32_e64 v26, s[100:101], v26, v30, s[100:101]
	v_cmp_le_u32_e64 s[100:101], s2, v20
	v_addc_co_u32_e32 v26, vcc, v26, v32, vcc
	v_addc_co_u32_e64 v26, s[98:99], v26, v34, s[98:99]
	v_addc_co_u32_e64 v26, s[100:101], v26, v36, s[100:101]
	s_nop 1
	v_add_u32_dpp v26, v26, v26 quad_perm:[1,0,3,2] row_mask:0xf bank_mask:0xf bound_ctrl:1
	s_nop 1
	v_add_u32_dpp v26, v26, v26 quad_perm:[2,3,0,1] row_mask:0xf bank_mask:0xf bound_ctrl:1
	s_nop 1
	v_add_u32_dpp v26, v26, v26 row_half_mirror row_mask:0xf bank_mask:0xf bound_ctrl:1
	s_nop 1
	v_add_u32_dpp v26, v26, v26 row_mirror row_mask:0xf bank_mask:0xf bound_ctrl:1
	s_nop 0
	v_readlane_b32 s0, v26, 0
	v_readlane_b32 s1, v26, 16
	v_readlane_b32 s3, v26, 32
	s_add_i32 s0, s1, s0
	v_readlane_b32 s4, v26, 48
	s_add_i32 s0, s0, s3
	s_add_i32 s3, s0, s4
	s_cmpk_lg_i32 s3, 0x100
	s_cselect_b64 s[0:1], -1, 0
	s_cmpk_gt_i32 s3, 0xff
	s_cselect_b32 s52, s2, s52
	s_add_i32 s2, s6, -1
	s_cmp_gt_i32 s6, 0
	s_mov_b32 s6, s2
	s_cselect_b64 s[2:3], -1, 0
	s_and_b64 s[0:1], s[0:1], s[2:3]
	s_and_b64 vcc, exec, s[0:1]
	s_cbranch_vccnz .LBB0_692

; DI int wave_isum(int v) {
;   v += __builtin_amdgcn_update_dpp(0, v, 0xB1, 0xf, 0xf, true);
;   v += __builtin_amdgcn_update_dpp(0, v, 0x4E, 0xf, 0xf, true);
;   v += __builtin_amdgcn_update_dpp(0, v, 0x141, 0xf, 0xf, true);
;   v += __builtin_amdgcn_update_dpp(0, v, 0x140, 0xf, 0xf, true);
;   return __builtin_amdgcn_readlane(v, 0) + __builtin_amdgcn_readlane(v, 16) + __builtin_amdgcn_readlane(v, 32) + __builtin_amdgcn_readlane(v, 48);
; template <int NJ>
; DI void b1_select(const float* sc, int nj, unsigned* mo) {
;     ...
;     unsigned E = M >> 23;
; #pragma unroll 1
;     for (int i = 0; i < 8; ++i) {
;       const unsigned cand = E << 23;
;       int c0 = 0, c1 = 0;
; #pragma unroll
;       for (int j = 0; j < NJ; ++j) { if (j & 1) c1 += (key[j] >= cand) ? 1 : 0; else c0 += (key[j] >= cand) ? 1 : 0; }
;       const int cnt = wave_isum(c0 + c1);
;       if (cnt >= 256) { T = cand; bit = 22; exact = (cnt == 256); break; }
;       if (E == 0u) break;
;       --E;
;     }
.LBB0_737:
	s_lshl_b32 s8, s7, 23
	v_cmp_le_u32_e32 vcc, s8, v2
	s_mov_b64 s[4:5], -1
	s_nop 0
	v_cndmask_b32_e64 v23, 0, 1, vcc
	v_cmp_le_u32_e32 vcc, s8, v7
	v_cmp_le_u32_e64 s[98:99], s8, v3
	v_cmp_le_u32_e64 s[100:101], s8, v9
	v_cndmask_b32_e64 v24, 0, 1, vcc
	v_cmp_le_u32_e32 vcc, s8, v6
	v_cndmask_b32_e64 v25, 0, 1, s[98:99]
	v_cmp_le_u32_e64 s[98:99], s8, v12
	v_cndmask_b32_e64 v26, 0, 1, s[100:101]
	v_cmp_le_u32_e64 s[100:101], s8, v11
	v_cndmask_b32_e64 v27, 0, 1, vcc
	v_cmp_le_u32_e32 vcc, s8, v17
	v_cndmask_b32_e64 v28, 0, 1, s[98:99]
	v_cmp_le_u32_e64 s[98:99], s8, v14
	v_cndmask_b32_e64 v29, 0, 1, s[100:101]
	v_cmp_le_u32_e64 s[100:101], s8, v19
	v_cndmask_b32_e64 v30, 0, 1, vcc
	v_cmp_le_u32_e32 vcc, s8, v4
	v_cndmask_b32_e64 v31, 0, 1, s[98:99]
	v_cmp_le_u32_e64 s[98:99], s8, v10
	v_cndmask_b32_e64 v32, 0, 1, s[100:101]
	v_cmp_le_u32_e64 s[100:101], s8, v15
	v_addc_co_u32_e32 v24, vcc, 0, v24, vcc
	v_cmp_le_u32_e32 vcc, s8, v18
	v_addc_co_u32_e64 v24, s[98:99], v24, v26, s[98:99]
	v_cmp_le_u32_e64 s[98:99], s8, v20
	v_addc_co_u32_e64 v24, s[100:101], v24, v28, s[100:101]
	v_cmp_le_u32_e64 s[100:101], s8, v21
	v_addc_co_u32_e32 v24, vcc, v24, v30, vcc
	v_cmp_le_u32_e32 vcc, s8, v5
	v_addc_co_u32_e64 v24, s[98:99], v24, v32, s[98:99]
	v_cmp_le_u32_e64 s[98:99], s8, v8
	v_addc_co_u32_e64 v23, s[100:101], v24, v23, s[100:101]
	v_cmp_le_u32_e64 s[100:101], s8, v13
	v_addc_co_u32_e32 v23, vcc, v23, v25, vcc
	v_cmp_le_u32_e32 vcc, s8, v16
	v_addc_co_u32_e64 v23, s[98:99], v23, v27, s[98:99]
	v_addc_co_u32_e64 v23, s[100:101], v23, v29, s[100:101]
	v_addc_co_u32_e32 v23, vcc, v23, v31, vcc
	s_nop 1
	v_add_u32_dpp v23, v23, v23 quad_perm:[1,0,3,2] row_mask:0xf bank_mask:0xf bound_ctrl:1
	s_nop 1
	v_add_u32_dpp v23, v23, v23 quad_perm:[2,3,0,1] row_mask:0xf bank_mask:0xf bound_ctrl:1
	s_nop 1
	v_add_u32_dpp v23, v23, v23 row_half_mirror row_mask:0xf bank_mask:0xf bound_ctrl:1
	s_nop 1
	v_add_u32_dpp v23, v23, v23 row_mirror row_mask:0xf bank_mask:0xf bound_ctrl:1
	s_nop 0
	v_readlane_b32 s2, v23, 0
	v_readlane_b32 s3, v23, 16
	s_add_i32 s2, s3, s2
	v_readlane_b32 s3, v23, 32
	s_add_i32 s10, s2, s3
	v_readlane_b32 s2, v23, 48
	s_add_i32 s10, s10, s2
	s_cmpk_lt_i32 s10, 0x100
	s_cbranch_scc0 .LBB0_740
	s_cmp_eq_u32 s7, 0
	v_sub_u32_e64 v23, s7, 1 clamp
	s_cselect_b64 s[2:3], -1, 0
	v_readfirstlane_b32 s9, v23
	s_cbranch_execz .LBB0_741

; DI int wave_isum(int v) {
;   v += __builtin_amdgcn_update_dpp(0, v, 0xB1, 0xf, 0xf, true);
;   v += __builtin_amdgcn_update_dpp(0, v, 0x4E, 0xf, 0xf, true);
;   v += __builtin_amdgcn_update_dpp(0, v, 0x141, 0xf, 0xf, true);
;   v += __builtin_amdgcn_update_dpp(0, v, 0x140, 0xf, 0xf, true);
;   return __builtin_amdgcn_readlane(v, 0) + __builtin_amdgcn_readlane(v, 16) + __builtin_amdgcn_readlane(v, 32) + __builtin_amdgcn_readlane(v, 48);
; template <int NJ>
; DI void b1_select(const float* sc, int nj, unsigned* mo) {
;     ...
; #pragma unroll 1
;     ...
;       const unsigned cand = T | (1u << bit);
;       int c0 = 0, c1 = 0;
; #pragma unroll
;       for (int j = 0; j < NJ; ++j) { if (j & 1) c1 += (key[j] >= cand) ? 1 : 0; else c0 += (key[j] >= cand) ? 1 : 0; }
;       const int cnt = wave_isum(c0 + c1);
;       if (cnt >= 256) { T = cand; if (cnt == 256) break; }
;     }
.LBB0_744:
	s_lshl_b32 s0, 1, s6
	s_or_b32 s2, s97, s0
	v_cmp_le_u32_e32 vcc, s2, v2
	v_cmp_le_u32_e64 s[98:99], s2, v7
	v_cmp_le_u32_e64 s[100:101], s2, v3
	v_cndmask_b32_e64 v22, 0, 1, vcc
	v_cmp_le_u32_e32 vcc, s2, v9
	v_cndmask_b32_e64 v23, 0, 1, s[98:99]
	v_cmp_le_u32_e64 s[98:99], s2, v6
	v_cndmask_b32_e64 v24, 0, 1, s[100:101]
	v_cmp_le_u32_e64 s[100:101], s2, v12
	v_cndmask_b32_e64 v25, 0, 1, vcc
	v_cmp_le_u32_e32 vcc, s2, v11
	v_cndmask_b32_e64 v26, 0, 1, s[98:99]
	v_cmp_le_u32_e64 s[98:99], s2, v17
	v_cndmask_b32_e64 v27, 0, 1, s[100:101]
	v_cmp_le_u32_e64 s[100:101], s2, v14
	v_cndmask_b32_e64 v28, 0, 1, vcc
	v_cmp_le_u32_e32 vcc, s2, v19
	v_cndmask_b32_e64 v29, 0, 1, s[98:99]
	v_cmp_le_u32_e64 s[98:99], s2, v4
	v_cndmask_b32_e64 v30, 0, 1, s[100:101]
	v_cmp_le_u32_e64 s[100:101], s2, v10
	v_cndmask_b32_e64 v31, 0, 1, vcc
	v_cmp_le_u32_e32 vcc, s2, v15
	v_addc_co_u32_e64 v23, s[98:99], 0, v23, s[98:99]
	v_cmp_le_u32_e64 s[98:99], s2, v18
	v_addc_co_u32_e64 v23, s[100:101], v23, v25, s[100:101]
	v_cmp_le_u32_e64 s[100:101], s2, v20
	v_addc_co_u32_e32 v23, vcc, v23, v27, vcc
	v_cmp_le_u32_e32 vcc, s2, v21
	v_addc_co_u32_e64 v23, s[98:99], v23, v29, s[98:99]
	v_cmp_le_u32_e64 s[98:99], s2, v5
	v_addc_co_u32_e64 v23, s[100:101], v23, v31, s[100:101]
	v_cmp_le_u32_e64 s[100:101], s2, v8
	v_addc_co_u32_e32 v22, vcc, v23, v22, vcc
	v_cmp_le_u32_e32 vcc, s2, v13
	v_addc_co_u32_e64 v22, s[98:99], v22, v24, s[98:99]
	v_cmp_le_u32_e64 s[98:99], s2, v16
	v_addc_co_u32_e64 v22, s[100:101], v22, v26, s[100:101]
	v_addc_co_u32_e32 v22, vcc, v22, v28, vcc
	v_addc_co_u32_e64 v22, s[98:99], v22, v30, s[98:99]
	s_nop 1
	v_add_u32_dpp v22, v22, v22 quad_perm:[1,0,3,2] row_mask:0xf bank_mask:0xf bound_ctrl:1
	s_nop 1
	v_add_u32_dpp v22, v22, v22 quad_perm:[2,3,0,1] row_mask:0xf bank_mask:0xf bound_ctrl:1
	s_nop 1
	v_add_u32_dpp v22, v22, v22 row_half_mirror row_mask:0xf bank_mask:0xf bound_ctrl:1
	s_nop 1
	v_add_u32_dpp v22, v22, v22 row_mirror row_mask:0xf bank_mask:0xf bound_ctrl:1
	s_nop 0
	v_readlane_b32 s0, v22, 0
	v_readlane_b32 s1, v22, 16
	v_readlane_b32 s3, v22, 32
	s_add_i32 s0, s1, s0
	v_readlane_b32 s4, v22, 48
	s_add_i32 s0, s0, s3
	s_add_i32 s3, s0, s4
	s_cmpk_lg_i32 s3, 0x100
	s_cselect_b64 s[0:1], -1, 0
	s_cmpk_gt_i32 s3, 0xff
	s_cselect_b32 s97, s2, s97
	s_add_i32 s2, s6, -1
	s_cmp_gt_i32 s6, 0
	s_mov_b32 s6, s2
	s_cselect_b64 s[2:3], -1, 0
	s_and_b64 s[0:1], s[0:1], s[2:3]
	s_and_b64 vcc, exec, s[0:1]
	s_cbranch_vccnz .LBB0_744

; DI int wave_isum(int v) {
;   v += __builtin_amdgcn_update_dpp(0, v, 0xB1, 0xf, 0xf, true);
;   v += __builtin_amdgcn_update_dpp(0, v, 0x4E, 0xf, 0xf, true);
;   v += __builtin_amdgcn_update_dpp(0, v, 0x141, 0xf, 0xf, true);
;   v += __builtin_amdgcn_update_dpp(0, v, 0x140, 0xf, 0xf, true);
;   return __builtin_amdgcn_readlane(v, 0) + __builtin_amdgcn_readlane(v, 16) + __builtin_amdgcn_readlane(v, 32) + __builtin_amdgcn_readlane(v, 48);
; template <int NJ>
; DI void b1_select(const float* sc, int nj, unsigned* mo) {
;     ...
;     unsigned E = M >> 23;
; #pragma unroll 1
;     for (int i = 0; i < 8; ++i) {
;       const unsigned cand = E << 23;
;       int c0 = 0, c1 = 0;
; #pragma unroll
;       for (int j = 0; j < NJ; ++j) { if (j & 1) c1 += (key[j] >= cand) ? 1 : 0; else c0 += (key[j] >= cand) ? 1 : 0; }
;       const int cnt = wave_isum(c0 + c1);
;       if (cnt >= 256) { T = cand; bit = 22; exact = (cnt == 256); break; }
;       if (E == 0u) break;
;       --E;
;     }
.LBB0_782:
	s_lshl_b32 s8, s7, 23
	v_cmp_le_u32_e32 vcc, s8, v2
	s_mov_b64 s[4:5], -1
	s_nop 0
	v_cndmask_b32_e64 v23, 0, 1, vcc
	v_cmp_le_u32_e32 vcc, s8, v8
	v_cmp_le_u32_e64 s[98:99], s8, v3
	v_cmp_le_u32_e64 s[100:101], s8, v9
	v_cndmask_b32_e64 v24, 0, 1, vcc
	v_cmp_le_u32_e32 vcc, s8, v6
	v_cndmask_b32_e64 v25, 0, 1, s[98:99]
	v_cmp_le_u32_e64 s[98:99], s8, v12
	v_cndmask_b32_e64 v26, 0, 1, s[100:101]
	v_cmp_le_u32_e64 s[100:101], s8, v10
	v_cndmask_b32_e64 v27, 0, 1, vcc
	v_cmp_le_u32_e32 vcc, s8, v16
	v_cndmask_b32_e64 v28, 0, 1, s[98:99]
	v_cmp_le_u32_e64 s[98:99], s8, v15
	v_cndmask_b32_e64 v29, 0, 1, s[100:101]
	v_cmp_le_u32_e64 s[100:101], s8, v19
	v_cndmask_b32_e64 v30, 0, 1, vcc
	v_cmp_le_u32_e32 vcc, s8, v4
	v_cndmask_b32_e64 v31, 0, 1, s[98:99]
	v_cmp_le_u32_e64 s[98:99], s8, v11
	v_cndmask_b32_e64 v32, 0, 1, s[100:101]
	v_cmp_le_u32_e64 s[100:101], s8, v14
	v_addc_co_u32_e32 v24, vcc, 0, v24, vcc
	v_cmp_le_u32_e32 vcc, s8, v18
	v_addc_co_u32_e64 v24, s[98:99], v24, v26, s[98:99]
	v_cmp_le_u32_e64 s[98:99], s8, v20
	v_addc_co_u32_e64 v24, s[100:101], v24, v28, s[100:101]
	v_cmp_le_u32_e64 s[100:101], s8, v21
	v_addc_co_u32_e32 v24, vcc, v24, v30, vcc
	v_cmp_le_u32_e32 vcc, s8, v5
	v_addc_co_u32_e64 v24, s[98:99], v24, v32, s[98:99]
	v_cmp_le_u32_e64 s[98:99], s8, v7
	v_addc_co_u32_e64 v23, s[100:101], v24, v23, s[100:101]
	v_cmp_le_u32_e64 s[100:101], s8, v13
	v_addc_co_u32_e32 v23, vcc, v23, v25, vcc
	v_cmp_le_u32_e32 vcc, s8, v17
	v_addc_co_u32_e64 v23, s[98:99], v23, v27, s[98:99]
	v_addc_co_u32_e64 v23, s[100:101], v23, v29, s[100:101]
	v_addc_co_u32_e32 v23, vcc, v23, v31, vcc
	s_nop 1
	v_add_u32_dpp v23, v23, v23 quad_perm:[1,0,3,2] row_mask:0xf bank_mask:0xf bound_ctrl:1
	s_nop 1
	v_add_u32_dpp v23, v23, v23 quad_perm:[2,3,0,1] row_mask:0xf bank_mask:0xf bound_ctrl:1
	s_nop 1
	v_add_u32_dpp v23, v23, v23 row_half_mirror row_mask:0xf bank_mask:0xf bound_ctrl:1
	s_nop 1
	v_add_u32_dpp v23, v23, v23 row_mirror row_mask:0xf bank_mask:0xf bound_ctrl:1
	s_nop 0
	v_readlane_b32 s2, v23, 0
	v_readlane_b32 s3, v23, 16
	s_add_i32 s2, s3, s2
	v_readlane_b32 s3, v23, 32
	s_add_i32 s10, s2, s3
	v_readlane_b32 s2, v23, 48
	s_add_i32 s10, s10, s2
	s_cmpk_lt_i32 s10, 0x100
	s_cbranch_scc0 .LBB0_785
	s_cmp_eq_u32 s7, 0
	v_sub_u32_e64 v23, s7, 1 clamp
	s_cselect_b64 s[2:3], -1, 0
	v_readfirstlane_b32 s9, v23
	s_cbranch_execz .LBB0_786

; DI int wave_isum(int v) {
;   v += __builtin_amdgcn_update_dpp(0, v, 0xB1, 0xf, 0xf, true);
;   v += __builtin_amdgcn_update_dpp(0, v, 0x4E, 0xf, 0xf, true);
;   v += __builtin_amdgcn_update_dpp(0, v, 0x141, 0xf, 0xf, true);
;   v += __builtin_amdgcn_update_dpp(0, v, 0x140, 0xf, 0xf, true);
;   return __builtin_amdgcn_readlane(v, 0) + __builtin_amdgcn_readlane(v, 16) + __builtin_amdgcn_readlane(v, 32) + __builtin_amdgcn_readlane(v, 48);
; template <int NJ>
; DI void b1_select(const float* sc, int nj, unsigned* mo) {
;     ...
; #pragma unroll 1
;     ...
;       const unsigned cand = T | (1u << bit);
;       int c0 = 0, c1 = 0;
; #pragma unroll
;       for (int j = 0; j < NJ; ++j) { if (j & 1) c1 += (key[j] >= cand) ? 1 : 0; else c0 += (key[j] >= cand) ? 1 : 0; }
;       const int cnt = wave_isum(c0 + c1);
;       if (cnt >= 256) { T = cand; if (cnt == 256) break; }
;     }
.LBB0_793:
	s_lshl_b32 s0, 1, s6
	s_or_b32 s2, s44, s0
	v_cmp_le_u32_e32 vcc, s2, v2
	v_cmp_le_u32_e64 s[98:99], s2, v8
	v_cmp_le_u32_e64 s[100:101], s2, v3
	v_cndmask_b32_e64 v22, 0, 1, vcc
	v_cmp_le_u32_e32 vcc, s2, v9
	v_cndmask_b32_e64 v23, 0, 1, s[98:99]
	v_cmp_le_u32_e64 s[98:99], s2, v6
	v_cndmask_b32_e64 v24, 0, 1, s[100:101]
	v_cmp_le_u32_e64 s[100:101], s2, v12
	v_cndmask_b32_e64 v25, 0, 1, vcc
	v_cmp_le_u32_e32 vcc, s2, v10
	v_cndmask_b32_e64 v26, 0, 1, s[98:99]
	v_cmp_le_u32_e64 s[98:99], s2, v16
	v_cndmask_b32_e64 v27, 0, 1, s[100:101]
	v_cmp_le_u32_e64 s[100:101], s2, v15
	v_cndmask_b32_e64 v28, 0, 1, vcc
	v_cmp_le_u32_e32 vcc, s2, v19
	v_cndmask_b32_e64 v29, 0, 1, s[98:99]
	v_cmp_le_u32_e64 s[98:99], s2, v4
	v_cndmask_b32_e64 v30, 0, 1, s[100:101]
	v_cmp_le_u32_e64 s[100:101], s2, v11
	v_cndmask_b32_e64 v31, 0, 1, vcc
	v_cmp_le_u32_e32 vcc, s2, v14
	v_addc_co_u32_e64 v23, s[98:99], 0, v23, s[98:99]
	v_cmp_le_u32_e64 s[98:99], s2, v18
	v_addc_co_u32_e64 v23, s[100:101], v23, v25, s[100:101]
	v_cmp_le_u32_e64 s[100:101], s2, v20
	v_addc_co_u32_e32 v23, vcc, v23, v27, vcc
	v_cmp_le_u32_e32 vcc, s2, v21
	v_addc_co_u32_e64 v23, s[98:99], v23, v29, s[98:99]
	v_cmp_le_u32_e64 s[98:99], s2, v5
	v_addc_co_u32_e64 v23, s[100:101], v23, v31, s[100:101]
	v_cmp_le_u32_e64 s[100:101], s2, v7
	v_addc_co_u32_e32 v22, vcc, v23, v22, vcc
	v_cmp_le_u32_e32 vcc, s2, v13
	v_addc_co_u32_e64 v22, s[98:99], v22, v24, s[98:99]
	v_cmp_le_u32_e64 s[98:99], s2, v17
	v_addc_co_u32_e64 v22, s[100:101], v22, v26, s[100:101]
	v_addc_co_u32_e32 v22, vcc, v22, v28, vcc
	v_addc_co_u32_e64 v22, s[98:99], v22, v30, s[98:99]
	s_nop 1
	v_add_u32_dpp v22, v22, v22 quad_perm:[1,0,3,2] row_mask:0xf bank_mask:0xf bound_ctrl:1
	s_nop 1
	v_add_u32_dpp v22, v22, v22 quad_perm:[2,3,0,1] row_mask:0xf bank_mask:0xf bound_ctrl:1
	s_nop 1
	v_add_u32_dpp v22, v22, v22 row_half_mirror row_mask:0xf bank_mask:0xf bound_ctrl:1
	s_nop 1
	v_add_u32_dpp v22, v22, v22 row_mirror row_mask:0xf bank_mask:0xf bound_ctrl:1
	s_nop 0
	v_readlane_b32 s0, v22, 0
	v_readlane_b32 s1, v22, 16
	v_readlane_b32 s3, v22, 32
	s_add_i32 s0, s1, s0
	v_readlane_b32 s4, v22, 48
	s_add_i32 s0, s0, s3
	s_add_i32 s3, s0, s4
	s_cmpk_lg_i32 s3, 0x100
	s_cselect_b64 s[0:1], -1, 0
	s_cmpk_gt_i32 s3, 0xff
	s_cselect_b32 s44, s2, s44
	s_add_i32 s2, s6, -1
	s_cmp_gt_i32 s6, 0
	s_mov_b32 s6, s2
	s_cselect_b64 s[2:3], -1, 0
	s_and_b64 s[0:1], s[0:1], s[2:3]
	s_and_b64 vcc, exec, s[0:1]
	s_cbranch_vccnz .LBB0_793

; DI int wave_isum(int v) {
;   v += __builtin_amdgcn_update_dpp(0, v, 0xB1, 0xf, 0xf, true);
;   v += __builtin_amdgcn_update_dpp(0, v, 0x4E, 0xf, 0xf, true);
;   v += __builtin_amdgcn_update_dpp(0, v, 0x141, 0xf, 0xf, true);
;   v += __builtin_amdgcn_update_dpp(0, v, 0x140, 0xf, 0xf, true);
;   return __builtin_amdgcn_readlane(v, 0) + __builtin_amdgcn_readlane(v, 16) + __builtin_amdgcn_readlane(v, 32) + __builtin_amdgcn_readlane(v, 48);
; template <int NJ>
; DI void b1_select(const float* sc, int nj, unsigned* mo) {
;     ...
;     unsigned E = M >> 23;
; #pragma unroll 1
;     for (int i = 0; i < 8; ++i) {
;       const unsigned cand = E << 23;
;       int c0 = 0, c1 = 0;
; #pragma unroll
;       for (int j = 0; j < NJ; ++j) { if (j & 1) c1 += (key[j] >= cand) ? 1 : 0; else c0 += (key[j] >= cand) ? 1 : 0; }
;       const int cnt = wave_isum(c0 + c1);
;       if (cnt >= 256) { T = cand; bit = 22; exact = (cnt == 256); break; }
;       if (E == 0u) break;
;       --E;
;     }
.LBB0_832:
	s_lshl_b32 s10, s9, 23
	v_cmp_le_u32_e32 vcc, s10, v2
	s_mov_b64 s[6:7], -1
	s_nop 0
	v_cndmask_b32_e64 v19, 0, 1, vcc
	v_cmp_le_u32_e32 vcc, s10, v7
	v_cmp_le_u32_e64 s[98:99], s10, v3
	v_cmp_le_u32_e64 s[100:101], s10, v9
	v_cndmask_b32_e64 v20, 0, 1, vcc
	v_cmp_le_u32_e32 vcc, s10, v6
	v_cndmask_b32_e64 v21, 0, 1, s[98:99]
	v_cmp_le_u32_e64 s[98:99], s10, v13
	v_cndmask_b32_e64 v22, 0, 1, s[100:101]
	v_cmp_le_u32_e64 s[100:101], s10, v10
	v_cndmask_b32_e64 v23, 0, 1, vcc
	v_cmp_le_u32_e32 vcc, s10, v15
	v_cndmask_b32_e64 v24, 0, 1, s[98:99]
	v_cmp_le_u32_e64 s[98:99], s10, v5
	v_cndmask_b32_e64 v25, 0, 1, s[100:101]
	v_cmp_le_u32_e64 s[100:101], s10, v11
	v_cndmask_b32_e64 v26, 0, 1, vcc
	v_cmp_le_u32_e32 vcc, s10, v14
	v_addc_co_u32_e64 v20, s[98:99], 0, v20, s[98:99]
	v_cmp_le_u32_e64 s[98:99], s10, v16
	v_addc_co_u32_e64 v20, s[100:101], v20, v22, s[100:101]
	v_cmp_le_u32_e64 s[100:101], s10, v17
	v_addc_co_u32_e32 v20, vcc, v20, v24, vcc
	v_cmp_le_u32_e32 vcc, s10, v4
	v_addc_co_u32_e64 v20, s[98:99], v20, v26, s[98:99]
	v_cmp_le_u32_e64 s[98:99], s10, v8
	v_addc_co_u32_e64 v19, s[100:101], v20, v19, s[100:101]
	v_cmp_le_u32_e64 s[100:101], s10, v12
	v_addc_co_u32_e32 v19, vcc, v19, v21, vcc
	v_addc_co_u32_e64 v19, s[98:99], v19, v23, s[98:99]
	v_addc_co_u32_e64 v19, s[100:101], v19, v25, s[100:101]
	s_nop 1
	v_add_u32_dpp v19, v19, v19 quad_perm:[1,0,3,2] row_mask:0xf bank_mask:0xf bound_ctrl:1
	s_nop 1
	v_add_u32_dpp v19, v19, v19 quad_perm:[2,3,0,1] row_mask:0xf bank_mask:0xf bound_ctrl:1
	s_nop 1
	v_add_u32_dpp v19, v19, v19 row_half_mirror row_mask:0xf bank_mask:0xf bound_ctrl:1
	s_nop 1
	v_add_u32_dpp v19, v19, v19 row_mirror row_mask:0xf bank_mask:0xf bound_ctrl:1
	s_nop 0
	v_readlane_b32 s2, v19, 0
	v_readlane_b32 s3, v19, 16
	s_add_i32 s2, s3, s2
	v_readlane_b32 s3, v19, 32
	s_add_i32 s12, s2, s3
	v_readlane_b32 s2, v19, 48
	s_add_i32 s12, s12, s2
	s_cmpk_lt_i32 s12, 0x100
	s_cbranch_scc0 .LBB0_835
	s_cmp_eq_u32 s9, 0
	v_sub_u32_e64 v19, s9, 1 clamp
	s_cselect_b64 s[2:3], -1, 0
	v_readfirstlane_b32 s11, v19
	s_cbranch_execz .LBB0_836

; DI int wave_isum(int v) {
;   v += __builtin_amdgcn_update_dpp(0, v, 0xB1, 0xf, 0xf, true);
;   v += __builtin_amdgcn_update_dpp(0, v, 0x4E, 0xf, 0xf, true);
;   v += __builtin_amdgcn_update_dpp(0, v, 0x141, 0xf, 0xf, true);
;   v += __builtin_amdgcn_update_dpp(0, v, 0x140, 0xf, 0xf, true);
;   return __builtin_amdgcn_readlane(v, 0) + __builtin_amdgcn_readlane(v, 16) + __builtin_amdgcn_readlane(v, 32) + __builtin_amdgcn_readlane(v, 48);
; template <int NJ>
; DI void b1_select(const float* sc, int nj, unsigned* mo) {
;     ...
; #pragma unroll 1
;     ...
;       const unsigned cand = T | (1u << bit);
;       int c0 = 0, c1 = 0;
; #pragma unroll
;       for (int j = 0; j < NJ; ++j) { if (j & 1) c1 += (key[j] >= cand) ? 1 : 0; else c0 += (key[j] >= cand) ? 1 : 0; }
;       const int cnt = wave_isum(c0 + c1);
;       if (cnt >= 256) { T = cand; if (cnt == 256) break; }
;     }
.LBB0_839:
	s_lshl_b32 s0, 1, s8
	s_or_b32 s2, s66, s0
	v_cmp_le_u32_e32 vcc, s2, v2
	v_cmp_le_u32_e64 s[98:99], s2, v7
	v_cmp_le_u32_e64 s[100:101], s2, v3
	v_cndmask_b32_e64 v18, 0, 1, vcc
	v_cmp_le_u32_e32 vcc, s2, v9
	v_cndmask_b32_e64 v19, 0, 1, s[98:99]
	v_cmp_le_u32_e64 s[98:99], s2, v6
	v_cndmask_b32_e64 v20, 0, 1, s[100:101]
	v_cmp_le_u32_e64 s[100:101], s2, v13
	v_cndmask_b32_e64 v21, 0, 1, vcc
	v_cmp_le_u32_e32 vcc, s2, v10
	v_cndmask_b32_e64 v22, 0, 1, s[98:99]
	v_cmp_le_u32_e64 s[98:99], s2, v15
	v_cndmask_b32_e64 v23, 0, 1, s[100:101]
	v_cmp_le_u32_e64 s[100:101], s2, v5
	v_cndmask_b32_e64 v24, 0, 1, vcc
	v_cmp_le_u32_e32 vcc, s2, v11
	v_cndmask_b32_e64 v25, 0, 1, s[98:99]
	v_cmp_le_u32_e64 s[98:99], s2, v14
	v_addc_co_u32_e64 v19, s[100:101], 0, v19, s[100:101]
	v_cmp_le_u32_e64 s[100:101], s2, v16
	v_addc_co_u32_e32 v19, vcc, v19, v21, vcc
	v_cmp_le_u32_e32 vcc, s2, v17
	v_addc_co_u32_e64 v19, s[98:99], v19, v23, s[98:99]
	v_cmp_le_u32_e64 s[98:99], s2, v4
	v_addc_co_u32_e64 v19, s[100:101], v19, v25, s[100:101]
	v_cmp_le_u32_e64 s[100:101], s2, v8
	v_addc_co_u32_e32 v18, vcc, v19, v18, vcc
	v_cmp_le_u32_e32 vcc, s2, v12
	v_addc_co_u32_e64 v18, s[98:99], v18, v20, s[98:99]
	v_addc_co_u32_e64 v18, s[100:101], v18, v22, s[100:101]
	v_addc_co_u32_e32 v18, vcc, v18, v24, vcc
	s_nop 1
	v_add_u32_dpp v18, v18, v18 quad_perm:[1,0,3,2] row_mask:0xf bank_mask:0xf bound_ctrl:1
	s_nop 1
	v_add_u32_dpp v18, v18, v18 quad_perm:[2,3,0,1] row_mask:0xf bank_mask:0xf bound_ctrl:1
	s_nop 1
	v_add_u32_dpp v18, v18, v18 row_half_mirror row_mask:0xf bank_mask:0xf bound_ctrl:1
	s_nop 1
	v_add_u32_dpp v18, v18, v18 row_mirror row_mask:0xf bank_mask:0xf bound_ctrl:1
	s_nop 0
	v_readlane_b32 s0, v18, 0
	v_readlane_b32 s1, v18, 16
	v_readlane_b32 s3, v18, 32
	s_add_i32 s0, s1, s0
	v_readlane_b32 s6, v18, 48
	s_add_i32 s0, s0, s3
	s_add_i32 s3, s0, s6
	s_cmpk_lg_i32 s3, 0x100
	s_cselect_b64 s[0:1], -1, 0
	s_cmpk_gt_i32 s3, 0xff
	s_cselect_b32 s66, s2, s66
	s_add_i32 s2, s8, -1
	s_cmp_gt_i32 s8, 0
	s_mov_b32 s8, s2
	s_cselect_b64 s[2:3], -1, 0
	s_and_b64 s[0:1], s[0:1], s[2:3]
	s_and_b64 vcc, exec, s[0:1]
	s_cbranch_vccnz .LBB0_839

; DI int wave_isum(int v) {
;   v += __builtin_amdgcn_update_dpp(0, v, 0xB1, 0xf, 0xf, true);
;   v += __builtin_amdgcn_update_dpp(0, v, 0x4E, 0xf, 0xf, true);
;   v += __builtin_amdgcn_update_dpp(0, v, 0x141, 0xf, 0xf, true);
;   v += __builtin_amdgcn_update_dpp(0, v, 0x140, 0xf, 0xf, true);
;   return __builtin_amdgcn_readlane(v, 0) + __builtin_amdgcn_readlane(v, 16) + __builtin_amdgcn_readlane(v, 32) + __builtin_amdgcn_readlane(v, 48);
; template <int NJ>
; DI void b1_select(const float* sc, int nj, unsigned* mo) {
;     ...
;     unsigned E = M >> 23;
; #pragma unroll 1
;     for (int i = 0; i < 8; ++i) {
;       const unsigned cand = E << 23;
;       int c0 = 0, c1 = 0;
; #pragma unroll
;       for (int j = 0; j < NJ; ++j) { if (j & 1) c1 += (key[j] >= cand) ? 1 : 0; else c0 += (key[j] >= cand) ? 1 : 0; }
;       const int cnt = wave_isum(c0 + c1);
;       if (cnt >= 256) { T = cand; bit = 22; exact = (cnt == 256); break; }
;       if (E == 0u) break;
;       --E;
;     }
.LBB0_873:
	s_lshl_b32 s8, s7, 23
	v_cmp_le_u32_e32 vcc, s8, v2
	s_mov_b64 s[4:5], -1
	s_nop 0
	v_cndmask_b32_e64 v19, 0, 1, vcc
	v_cmp_le_u32_e32 vcc, s8, v8
	v_cmp_le_u32_e64 s[98:99], s8, v4
	v_cmp_le_u32_e64 s[100:101], s8, v9
	v_cndmask_b32_e64 v20, 0, 1, vcc
	v_cmp_le_u32_e32 vcc, s8, v6
	v_cndmask_b32_e64 v21, 0, 1, s[98:99]
	v_cmp_le_u32_e64 s[98:99], s8, v13
	v_cndmask_b32_e64 v22, 0, 1, s[100:101]
	v_cmp_le_u32_e64 s[100:101], s8, v10
	v_cndmask_b32_e64 v23, 0, 1, vcc
	v_cmp_le_u32_e32 vcc, s8, v15
	v_cndmask_b32_e64 v24, 0, 1, s[98:99]
	v_cmp_le_u32_e64 s[98:99], s8, v3
	v_cndmask_b32_e64 v25, 0, 1, s[100:101]
	v_cmp_le_u32_e64 s[100:101], s8, v11
	v_cndmask_b32_e64 v26, 0, 1, vcc
	v_cmp_le_u32_e32 vcc, s8, v14
	v_addc_co_u32_e64 v20, s[98:99], 0, v20, s[98:99]
	v_cmp_le_u32_e64 s[98:99], s8, v16
	v_addc_co_u32_e64 v20, s[100:101], v20, v22, s[100:101]
	v_cmp_le_u32_e64 s[100:101], s8, v17
	v_addc_co_u32_e32 v20, vcc, v20, v24, vcc
	v_cmp_le_u32_e32 vcc, s8, v5
	v_addc_co_u32_e64 v20, s[98:99], v20, v26, s[98:99]
	v_cmp_le_u32_e64 s[98:99], s8, v7
	v_addc_co_u32_e64 v19, s[100:101], v20, v19, s[100:101]
	v_cmp_le_u32_e64 s[100:101], s8, v12
	v_addc_co_u32_e32 v19, vcc, v19, v21, vcc
	v_addc_co_u32_e64 v19, s[98:99], v19, v23, s[98:99]
	v_addc_co_u32_e64 v19, s[100:101], v19, v25, s[100:101]
	s_nop 1
	v_add_u32_dpp v19, v19, v19 quad_perm:[1,0,3,2] row_mask:0xf bank_mask:0xf bound_ctrl:1
	s_nop 1
	v_add_u32_dpp v19, v19, v19 quad_perm:[2,3,0,1] row_mask:0xf bank_mask:0xf bound_ctrl:1
	s_nop 1
	v_add_u32_dpp v19, v19, v19 row_half_mirror row_mask:0xf bank_mask:0xf bound_ctrl:1
	s_nop 1
	v_add_u32_dpp v19, v19, v19 row_mirror row_mask:0xf bank_mask:0xf bound_ctrl:1
	s_nop 0
	v_readlane_b32 s2, v19, 0
	v_readlane_b32 s3, v19, 16
	s_add_i32 s2, s3, s2
	v_readlane_b32 s3, v19, 32
	s_add_i32 s10, s2, s3
	v_readlane_b32 s2, v19, 48
	s_add_i32 s10, s10, s2
	s_cmpk_lt_i32 s10, 0x100
	s_cbranch_scc0 .LBB0_876
	s_cmp_eq_u32 s7, 0
	v_sub_u32_e64 v19, s7, 1 clamp
	s_cselect_b64 s[2:3], -1, 0
	v_readfirstlane_b32 s9, v19
	s_cbranch_execz .LBB0_877

; DI int wave_isum(int v) {
;   v += __builtin_amdgcn_update_dpp(0, v, 0xB1, 0xf, 0xf, true);
;   v += __builtin_amdgcn_update_dpp(0, v, 0x4E, 0xf, 0xf, true);
;   v += __builtin_amdgcn_update_dpp(0, v, 0x141, 0xf, 0xf, true);
;   v += __builtin_amdgcn_update_dpp(0, v, 0x140, 0xf, 0xf, true);
;   return __builtin_amdgcn_readlane(v, 0) + __builtin_amdgcn_readlane(v, 16) + __builtin_amdgcn_readlane(v, 32) + __builtin_amdgcn_readlane(v, 48);
; template <int NJ>
; DI void b1_select(const float* sc, int nj, unsigned* mo) {
;     ...
; #pragma unroll 1
;     ...
;       const unsigned cand = T | (1u << bit);
;       int c0 = 0, c1 = 0;
; #pragma unroll
;       for (int j = 0; j < NJ; ++j) { if (j & 1) c1 += (key[j] >= cand) ? 1 : 0; else c0 += (key[j] >= cand) ? 1 : 0; }
;       const int cnt = wave_isum(c0 + c1);
;       if (cnt >= 256) { T = cand; if (cnt == 256) break; }
;     }
.LBB0_880:
	s_lshl_b32 s0, 1, s6
	s_or_b32 s2, s36, s0
	v_cmp_le_u32_e32 vcc, s2, v2
	v_cmp_le_u32_e64 s[98:99], s2, v8
	v_cmp_le_u32_e64 s[100:101], s2, v4
	v_cndmask_b32_e64 v18, 0, 1, vcc
	v_cmp_le_u32_e32 vcc, s2, v9
	v_cndmask_b32_e64 v19, 0, 1, s[98:99]
	v_cmp_le_u32_e64 s[98:99], s2, v6
	v_cndmask_b32_e64 v20, 0, 1, s[100:101]
	v_cmp_le_u32_e64 s[100:101], s2, v13
	v_cndmask_b32_e64 v21, 0, 1, vcc
	v_cmp_le_u32_e32 vcc, s2, v10
	v_cndmask_b32_e64 v22, 0, 1, s[98:99]
	v_cmp_le_u32_e64 s[98:99], s2, v15
	v_cndmask_b32_e64 v23, 0, 1, s[100:101]
	v_cmp_le_u32_e64 s[100:101], s2, v3
	v_cndmask_b32_e64 v24, 0, 1, vcc
	v_cmp_le_u32_e32 vcc, s2, v11
	v_cndmask_b32_e64 v25, 0, 1, s[98:99]
	v_cmp_le_u32_e64 s[98:99], s2, v14
	v_addc_co_u32_e64 v19, s[100:101], 0, v19, s[100:101]
	v_cmp_le_u32_e64 s[100:101], s2, v16
	v_addc_co_u32_e32 v19, vcc, v19, v21, vcc
	v_cmp_le_u32_e32 vcc, s2, v17
	v_addc_co_u32_e64 v19, s[98:99], v19, v23, s[98:99]
	v_cmp_le_u32_e64 s[98:99], s2, v5
	v_addc_co_u32_e64 v19, s[100:101], v19, v25, s[100:101]
	v_cmp_le_u32_e64 s[100:101], s2, v7
	v_addc_co_u32_e32 v18, vcc, v19, v18, vcc
	v_cmp_le_u32_e32 vcc, s2, v12
	v_addc_co_u32_e64 v18, s[98:99], v18, v20, s[98:99]
	v_addc_co_u32_e64 v18, s[100:101], v18, v22, s[100:101]
	v_addc_co_u32_e32 v18, vcc, v18, v24, vcc
	s_nop 1
	v_add_u32_dpp v18, v18, v18 quad_perm:[1,0,3,2] row_mask:0xf bank_mask:0xf bound_ctrl:1
	s_nop 1
	v_add_u32_dpp v18, v18, v18 quad_perm:[2,3,0,1] row_mask:0xf bank_mask:0xf bound_ctrl:1
	s_nop 1
	v_add_u32_dpp v18, v18, v18 row_half_mirror row_mask:0xf bank_mask:0xf bound_ctrl:1
	s_nop 1
	v_add_u32_dpp v18, v18, v18 row_mirror row_mask:0xf bank_mask:0xf bound_ctrl:1
	s_nop 0
	v_readlane_b32 s0, v18, 0
	v_readlane_b32 s1, v18, 16
	v_readlane_b32 s3, v18, 32
	s_add_i32 s0, s1, s0
	v_readlane_b32 s4, v18, 48
	s_add_i32 s0, s0, s3
	s_add_i32 s3, s0, s4
	s_cmpk_lg_i32 s3, 0x100
	s_cselect_b64 s[0:1], -1, 0
	s_cmpk_gt_i32 s3, 0xff
	s_cselect_b32 s36, s2, s36
	s_add_i32 s2, s6, -1
	s_cmp_gt_i32 s6, 0
	s_mov_b32 s6, s2
	s_cselect_b64 s[2:3], -1, 0
	s_and_b64 s[0:1], s[0:1], s[2:3]
	s_and_b64 vcc, exec, s[0:1]
	s_cbranch_vccnz .LBB0_880

; DI int wave_isum(int v) {
;   v += __builtin_amdgcn_update_dpp(0, v, 0xB1, 0xf, 0xf, true);
;   v += __builtin_amdgcn_update_dpp(0, v, 0x4E, 0xf, 0xf, true);
;   v += __builtin_amdgcn_update_dpp(0, v, 0x141, 0xf, 0xf, true);
;   v += __builtin_amdgcn_update_dpp(0, v, 0x140, 0xf, 0xf, true);
;   return __builtin_amdgcn_readlane(v, 0) + __builtin_amdgcn_readlane(v, 16) + __builtin_amdgcn_readlane(v, 32) + __builtin_amdgcn_readlane(v, 48);
; template <int NJ>
; DI void b1_select(const float* sc, int nj, unsigned* mo) {
;     ...
;     unsigned E = M >> 23;
; #pragma unroll 1
;     for (int i = 0; i < 8; ++i) {
;       const unsigned cand = E << 23;
;       int c0 = 0, c1 = 0;
; #pragma unroll
;       for (int j = 0; j < NJ; ++j) { if (j & 1) c1 += (key[j] >= cand) ? 1 : 0; else c0 += (key[j] >= cand) ? 1 : 0; }
;       const int cnt = wave_isum(c0 + c1);
;       if (cnt >= 256) { T = cand; bit = 22; exact = (cnt == 256); break; }
;       if (E == 0u) break;
;       --E;
;     }
.LBB0_908:
	s_lshl_b32 s10, s9, 23
	v_cmp_le_u32_e32 vcc, s10, v2
	s_mov_b64 s[6:7], -1
	s_nop 0
	v_cndmask_b32_e64 v15, 0, 1, vcc
	v_cmp_le_u32_e32 vcc, s10, v7
	v_cmp_le_u32_e64 s[98:99], s10, v3
	v_cmp_le_u32_e64 s[100:101], s10, v9
	v_cndmask_b32_e64 v16, 0, 1, vcc
	v_cmp_le_u32_e32 vcc, s10, v6
	v_cndmask_b32_e64 v17, 0, 1, s[98:99]
	v_cmp_le_u32_e64 s[98:99], s10, v11
	v_cndmask_b32_e64 v18, 0, 1, s[100:101]
	v_cmp_le_u32_e64 s[100:101], s10, v5
	v_cndmask_b32_e64 v19, 0, 1, vcc
	v_cmp_le_u32_e32 vcc, s10, v10
	v_cndmask_b32_e64 v20, 0, 1, s[98:99]
	v_cmp_le_u32_e64 s[98:99], s10, v12
	v_addc_co_u32_e64 v16, s[100:101], 0, v16, s[100:101]
	v_cmp_le_u32_e64 s[100:101], s10, v13
	v_addc_co_u32_e32 v16, vcc, v16, v18, vcc
	v_cmp_le_u32_e32 vcc, s10, v4
	v_addc_co_u32_e64 v16, s[98:99], v16, v20, s[98:99]
	v_cmp_le_u32_e64 s[98:99], s10, v8
	v_addc_co_u32_e64 v15, s[100:101], v16, v15, s[100:101]
	v_addc_co_u32_e32 v15, vcc, v15, v17, vcc
	v_addc_co_u32_e64 v15, s[98:99], v15, v19, s[98:99]
	s_nop 1
	v_add_u32_dpp v15, v15, v15 quad_perm:[1,0,3,2] row_mask:0xf bank_mask:0xf bound_ctrl:1
	s_nop 1
	v_add_u32_dpp v15, v15, v15 quad_perm:[2,3,0,1] row_mask:0xf bank_mask:0xf bound_ctrl:1
	s_nop 1
	v_add_u32_dpp v15, v15, v15 row_half_mirror row_mask:0xf bank_mask:0xf bound_ctrl:1
	s_nop 1
	v_add_u32_dpp v15, v15, v15 row_mirror row_mask:0xf bank_mask:0xf bound_ctrl:1
	s_nop 0
	v_readlane_b32 s2, v15, 0
	v_readlane_b32 s3, v15, 16
	s_add_i32 s2, s3, s2
	v_readlane_b32 s3, v15, 32
	s_add_i32 s12, s2, s3
	v_readlane_b32 s2, v15, 48
	s_add_i32 s12, s12, s2
	s_cmpk_lt_i32 s12, 0x100
	s_cbranch_scc0 .LBB0_911
	s_cmp_eq_u32 s9, 0
	v_sub_u32_e64 v15, s9, 1 clamp
	s_cselect_b64 s[2:3], -1, 0
	v_readfirstlane_b32 s11, v15
	s_cbranch_execz .LBB0_912

; DI int wave_isum(int v) {
;   v += __builtin_amdgcn_update_dpp(0, v, 0xB1, 0xf, 0xf, true);
;   v += __builtin_amdgcn_update_dpp(0, v, 0x4E, 0xf, 0xf, true);
;   v += __builtin_amdgcn_update_dpp(0, v, 0x141, 0xf, 0xf, true);
;   v += __builtin_amdgcn_update_dpp(0, v, 0x140, 0xf, 0xf, true);
;   return __builtin_amdgcn_readlane(v, 0) + __builtin_amdgcn_readlane(v, 16) + __builtin_amdgcn_readlane(v, 32) + __builtin_amdgcn_readlane(v, 48);
; template <int NJ>
; DI void b1_select(const float* sc, int nj, unsigned* mo) {
;     ...
; #pragma unroll 1
;     ...
;       const unsigned cand = T | (1u << bit);
;       int c0 = 0, c1 = 0;
; #pragma unroll
;       for (int j = 0; j < NJ; ++j) { if (j & 1) c1 += (key[j] >= cand) ? 1 : 0; else c0 += (key[j] >= cand) ? 1 : 0; }
;       const int cnt = wave_isum(c0 + c1);
;       if (cnt >= 256) { T = cand; if (cnt == 256) break; }
;     }
.LBB0_915:
	s_lshl_b32 s0, 1, s8
	s_or_b32 s2, s50, s0
	v_cmp_le_u32_e32 vcc, s2, v2
	v_cmp_le_u32_e64 s[98:99], s2, v7
	v_cmp_le_u32_e64 s[100:101], s2, v3
	v_cndmask_b32_e64 v14, 0, 1, vcc
	v_cmp_le_u32_e32 vcc, s2, v9
	v_cndmask_b32_e64 v15, 0, 1, s[98:99]
	v_cmp_le_u32_e64 s[98:99], s2, v6
	v_cndmask_b32_e64 v16, 0, 1, s[100:101]
	v_cmp_le_u32_e64 s[100:101], s2, v11
	v_cndmask_b32_e64 v17, 0, 1, vcc
	v_cmp_le_u32_e32 vcc, s2, v5
	v_cndmask_b32_e64 v18, 0, 1, s[98:99]
	v_cmp_le_u32_e64 s[98:99], s2, v10
	v_cndmask_b32_e64 v19, 0, 1, s[100:101]
	v_cmp_le_u32_e64 s[100:101], s2, v12
	v_addc_co_u32_e32 v15, vcc, 0, v15, vcc
	v_cmp_le_u32_e32 vcc, s2, v13
	v_addc_co_u32_e64 v15, s[98:99], v15, v17, s[98:99]
	v_cmp_le_u32_e64 s[98:99], s2, v4
	v_addc_co_u32_e64 v15, s[100:101], v15, v19, s[100:101]
	v_cmp_le_u32_e64 s[100:101], s2, v8
	v_addc_co_u32_e32 v14, vcc, v15, v14, vcc
	v_addc_co_u32_e64 v14, s[98:99], v14, v16, s[98:99]
	v_addc_co_u32_e64 v14, s[100:101], v14, v18, s[100:101]
	s_nop 1
	v_add_u32_dpp v14, v14, v14 quad_perm:[1,0,3,2] row_mask:0xf bank_mask:0xf bound_ctrl:1
	s_nop 1
	v_add_u32_dpp v14, v14, v14 quad_perm:[2,3,0,1] row_mask:0xf bank_mask:0xf bound_ctrl:1
	s_nop 1
	v_add_u32_dpp v14, v14, v14 row_half_mirror row_mask:0xf bank_mask:0xf bound_ctrl:1
	s_nop 1
	v_add_u32_dpp v14, v14, v14 row_mirror row_mask:0xf bank_mask:0xf bound_ctrl:1
	s_nop 0
	v_readlane_b32 s0, v14, 0
	v_readlane_b32 s1, v14, 16
	v_readlane_b32 s3, v14, 32
	s_add_i32 s0, s1, s0
	v_readlane_b32 s6, v14, 48
	s_add_i32 s0, s0, s3
	s_add_i32 s3, s0, s6
	s_cmpk_lg_i32 s3, 0x100
	s_cselect_b64 s[0:1], -1, 0
	s_cmpk_gt_i32 s3, 0xff
	s_cselect_b32 s50, s2, s50
	s_add_i32 s2, s8, -1
	s_cmp_gt_i32 s8, 0
	s_mov_b32 s8, s2
	s_cselect_b64 s[2:3], -1, 0
	s_and_b64 s[0:1], s[0:1], s[2:3]
	s_and_b64 vcc, exec, s[0:1]
	s_cbranch_vccnz .LBB0_915

; DI int wave_isum(int v) {
;   v += __builtin_amdgcn_update_dpp(0, v, 0xB1, 0xf, 0xf, true);
;   v += __builtin_amdgcn_update_dpp(0, v, 0x4E, 0xf, 0xf, true);
;   v += __builtin_amdgcn_update_dpp(0, v, 0x141, 0xf, 0xf, true);
;   v += __builtin_amdgcn_update_dpp(0, v, 0x140, 0xf, 0xf, true);
;   return __builtin_amdgcn_readlane(v, 0) + __builtin_amdgcn_readlane(v, 16) + __builtin_amdgcn_readlane(v, 32) + __builtin_amdgcn_readlane(v, 48);
; template <int NJ>
; DI void b1_select(const float* sc, int nj, unsigned* mo) {
;     ...
;     unsigned E = M >> 23;
; #pragma unroll 1
;     for (int i = 0; i < 8; ++i) {
;       const unsigned cand = E << 23;
;       int c0 = 0, c1 = 0;
; #pragma unroll
;       for (int j = 0; j < NJ; ++j) { if (j & 1) c1 += (key[j] >= cand) ? 1 : 0; else c0 += (key[j] >= cand) ? 1 : 0; }
;       const int cnt = wave_isum(c0 + c1);
;       if (cnt >= 256) { T = cand; bit = 22; exact = (cnt == 256); break; }
;       if (E == 0u) break;
;       --E;
;     }
.LBB0_937:
	s_lshl_b32 s8, s7, 23
	v_cmp_le_u32_e32 vcc, s8, v2
	s_mov_b64 s[4:5], -1
	s_nop 0
	v_cndmask_b32_e64 v15, 0, 1, vcc
	v_cmp_le_u32_e32 vcc, s8, v7
	v_cmp_le_u32_e64 s[98:99], s8, v3
	v_cmp_le_u32_e64 s[100:101], s8, v9
	v_cndmask_b32_e64 v16, 0, 1, vcc
	v_cmp_le_u32_e32 vcc, s8, v6
	v_cndmask_b32_e64 v17, 0, 1, s[98:99]
	v_cmp_le_u32_e64 s[98:99], s8, v11
	v_cndmask_b32_e64 v18, 0, 1, s[100:101]
	v_cmp_le_u32_e64 s[100:101], s8, v5
	v_cndmask_b32_e64 v19, 0, 1, vcc
	v_cmp_le_u32_e32 vcc, s8, v10
	v_cndmask_b32_e64 v20, 0, 1, s[98:99]
	v_cmp_le_u32_e64 s[98:99], s8, v12
	v_addc_co_u32_e64 v16, s[100:101], 0, v16, s[100:101]
	v_cmp_le_u32_e64 s[100:101], s8, v13
	v_addc_co_u32_e32 v16, vcc, v16, v18, vcc
	v_cmp_le_u32_e32 vcc, s8, v4
	v_addc_co_u32_e64 v16, s[98:99], v16, v20, s[98:99]
	v_cmp_le_u32_e64 s[98:99], s8, v8
	v_addc_co_u32_e64 v15, s[100:101], v16, v15, s[100:101]
	v_addc_co_u32_e32 v15, vcc, v15, v17, vcc
	v_addc_co_u32_e64 v15, s[98:99], v15, v19, s[98:99]
	s_nop 1
	v_add_u32_dpp v15, v15, v15 quad_perm:[1,0,3,2] row_mask:0xf bank_mask:0xf bound_ctrl:1
	s_nop 1
	v_add_u32_dpp v15, v15, v15 quad_perm:[2,3,0,1] row_mask:0xf bank_mask:0xf bound_ctrl:1
	s_nop 1
	v_add_u32_dpp v15, v15, v15 row_half_mirror row_mask:0xf bank_mask:0xf bound_ctrl:1
	s_nop 1
	v_add_u32_dpp v15, v15, v15 row_mirror row_mask:0xf bank_mask:0xf bound_ctrl:1
	s_nop 0
	v_readlane_b32 s2, v15, 0
	v_readlane_b32 s3, v15, 16
	s_add_i32 s2, s3, s2
	v_readlane_b32 s3, v15, 32
	s_add_i32 s10, s2, s3
	v_readlane_b32 s2, v15, 48
	s_add_i32 s10, s10, s2
	s_cmpk_lt_i32 s10, 0x100
	s_cbranch_scc0 .LBB0_940
	s_cmp_eq_u32 s7, 0
	v_sub_u32_e64 v15, s7, 1 clamp
	s_cselect_b64 s[2:3], -1, 0
	v_readfirstlane_b32 s9, v15
	s_cbranch_execz .LBB0_941

; DI int wave_isum(int v) {
;   v += __builtin_amdgcn_update_dpp(0, v, 0xB1, 0xf, 0xf, true);
;   v += __builtin_amdgcn_update_dpp(0, v, 0x4E, 0xf, 0xf, true);
;   v += __builtin_amdgcn_update_dpp(0, v, 0x141, 0xf, 0xf, true);
;   v += __builtin_amdgcn_update_dpp(0, v, 0x140, 0xf, 0xf, true);
;   return __builtin_amdgcn_readlane(v, 0) + __builtin_amdgcn_readlane(v, 16) + __builtin_amdgcn_readlane(v, 32) + __builtin_amdgcn_readlane(v, 48);
; template <int NJ>
; DI void b1_select(const float* sc, int nj, unsigned* mo) {
;     ...
; #pragma unroll 1
;     ...
;       const unsigned cand = T | (1u << bit);
;       int c0 = 0, c1 = 0;
; #pragma unroll
;       for (int j = 0; j < NJ; ++j) { if (j & 1) c1 += (key[j] >= cand) ? 1 : 0; else c0 += (key[j] >= cand) ? 1 : 0; }
;       const int cnt = wave_isum(c0 + c1);
;       if (cnt >= 256) { T = cand; if (cnt == 256) break; }
;     }
.LBB0_948:
	s_lshl_b32 s0, 1, s6
	s_or_b32 s2, s26, s0
	v_cmp_le_u32_e32 vcc, s2, v2
	v_cmp_le_u32_e64 s[98:99], s2, v7
	v_cmp_le_u32_e64 s[100:101], s2, v3
	v_cndmask_b32_e64 v14, 0, 1, vcc
	v_cmp_le_u32_e32 vcc, s2, v9
	v_cndmask_b32_e64 v15, 0, 1, s[98:99]
	v_cmp_le_u32_e64 s[98:99], s2, v6
	v_cndmask_b32_e64 v16, 0, 1, s[100:101]
	v_cmp_le_u32_e64 s[100:101], s2, v11
	v_cndmask_b32_e64 v17, 0, 1, vcc
	v_cmp_le_u32_e32 vcc, s2, v5
	v_cndmask_b32_e64 v18, 0, 1, s[98:99]
	v_cmp_le_u32_e64 s[98:99], s2, v10
	v_cndmask_b32_e64 v19, 0, 1, s[100:101]
	v_cmp_le_u32_e64 s[100:101], s2, v12
	v_addc_co_u32_e32 v15, vcc, 0, v15, vcc
	v_cmp_le_u32_e32 vcc, s2, v13
	v_addc_co_u32_e64 v15, s[98:99], v15, v17, s[98:99]
	v_cmp_le_u32_e64 s[98:99], s2, v4
	v_addc_co_u32_e64 v15, s[100:101], v15, v19, s[100:101]
	v_cmp_le_u32_e64 s[100:101], s2, v8
	v_addc_co_u32_e32 v14, vcc, v15, v14, vcc
	v_addc_co_u32_e64 v14, s[98:99], v14, v16, s[98:99]
	v_addc_co_u32_e64 v14, s[100:101], v14, v18, s[100:101]
	s_nop 1
	v_add_u32_dpp v14, v14, v14 quad_perm:[1,0,3,2] row_mask:0xf bank_mask:0xf bound_ctrl:1
	s_nop 1
	v_add_u32_dpp v14, v14, v14 quad_perm:[2,3,0,1] row_mask:0xf bank_mask:0xf bound_ctrl:1
	s_nop 1
	v_add_u32_dpp v14, v14, v14 row_half_mirror row_mask:0xf bank_mask:0xf bound_ctrl:1
	s_nop 1
	v_add_u32_dpp v14, v14, v14 row_mirror row_mask:0xf bank_mask:0xf bound_ctrl:1
	s_nop 0
	v_readlane_b32 s0, v14, 0
	v_readlane_b32 s1, v14, 16
	v_readlane_b32 s3, v14, 32
	s_add_i32 s0, s1, s0
	v_readlane_b32 s4, v14, 48
	s_add_i32 s0, s0, s3
	s_add_i32 s3, s0, s4
	s_cmpk_lg_i32 s3, 0x100
	s_cselect_b64 s[0:1], -1, 0
	s_cmpk_gt_i32 s3, 0xff
	s_cselect_b32 s26, s2, s26
	s_add_i32 s2, s6, -1
	s_cmp_gt_i32 s6, 0
	s_mov_b32 s6, s2
	s_cselect_b64 s[2:3], -1, 0
	s_and_b64 s[0:1], s[0:1], s[2:3]
	s_and_b64 vcc, exec, s[0:1]
	s_cbranch_vccnz .LBB0_948

; DI int wave_isum(int v) {
;   v += __builtin_amdgcn_update_dpp(0, v, 0xB1, 0xf, 0xf, true);
;   v += __builtin_amdgcn_update_dpp(0, v, 0x4E, 0xf, 0xf, true);
;   v += __builtin_amdgcn_update_dpp(0, v, 0x141, 0xf, 0xf, true);
;   v += __builtin_amdgcn_update_dpp(0, v, 0x140, 0xf, 0xf, true);
;   return __builtin_amdgcn_readlane(v, 0) + __builtin_amdgcn_readlane(v, 16) + __builtin_amdgcn_readlane(v, 32) + __builtin_amdgcn_readlane(v, 48);
; template <int NJ>
; DI void b1_select(const float* sc, int nj, unsigned* mo) {
;     ...
;     unsigned E = M >> 23;
; #pragma unroll 1
;     for (int i = 0; i < 8; ++i) {
;       const unsigned cand = E << 23;
;       int c0 = 0, c1 = 0;
; #pragma unroll
;       for (int j = 0; j < NJ; ++j) { if (j & 1) c1 += (key[j] >= cand) ? 1 : 0; else c0 += (key[j] >= cand) ? 1 : 0; }
;       const int cnt = wave_isum(c0 + c1);
;       if (cnt >= 256) { T = cand; bit = 22; exact = (cnt == 256); break; }
;       if (E == 0u) break;
;       --E;
;     }
.LBB0_1019:
	s_lshl_b32 s8, s7, 23
	v_cmp_le_u32_e32 vcc, s8, v2
	s_mov_b64 s[4:5], -1
	s_nop 0
	v_cndmask_b32_e64 v35, 0, 1, vcc
	v_cmp_le_u32_e32 vcc, s8, v7
	v_cmp_le_u32_e64 s[98:99], s8, v3
	v_cmp_le_u32_e64 s[100:101], s8, v9
	v_cndmask_b32_e64 v36, 0, 1, vcc
	v_cmp_le_u32_e32 vcc, s8, v6
	v_cndmask_b32_e64 v37, 0, 1, s[98:99]
	v_cmp_le_u32_e64 s[98:99], s8, v13
	v_cndmask_b32_e64 v38, 0, 1, s[100:101]
	v_cmp_le_u32_e64 s[100:101], s8, v10
	v_cndmask_b32_e64 v39, 0, 1, vcc
	v_cmp_le_u32_e32 vcc, s8, v17
	v_cndmask_b32_e64 v40, 0, 1, s[98:99]
	v_cmp_le_u32_e64 s[98:99], s8, v14
	v_cndmask_b32_e64 v41, 0, 1, s[100:101]
	v_cmp_le_u32_e64 s[100:101], s8, v21
	v_cndmask_b32_e64 v42, 0, 1, vcc
	v_cmp_le_u32_e32 vcc, s8, v18
	v_cndmask_b32_e64 v43, 0, 1, s[98:99]
	v_cmp_le_u32_e64 s[98:99], s8, v26
	v_cndmask_b32_e64 v44, 0, 1, s[100:101]
	v_cmp_le_u32_e64 s[100:101], s8, v22
	v_cndmask_b32_e64 v45, 0, 1, vcc
	v_cmp_le_u32_e32 vcc, s8, v29
	v_cndmask_b32_e64 v46, 0, 1, s[98:99]
	v_cmp_le_u32_e64 s[98:99], s8, v25
	v_cndmask_b32_e64 v47, 0, 1, s[100:101]
	v_cmp_le_u32_e64 s[100:101], s8, v31
	v_cndmask_b32_e64 v48, 0, 1, vcc
	v_cmp_le_u32_e32 vcc, s8, v5
	v_cndmask_b32_e64 v49, 0, 1, s[98:99]
	v_cmp_le_u32_e64 s[98:99], s8, v11
	v_cndmask_b32_e64 v50, 0, 1, s[100:101]
	v_cmp_le_u32_e64 s[100:101], s8, v15
	v_addc_co_u32_e32 v36, vcc, 0, v36, vcc
	v_cmp_le_u32_e32 vcc, s8, v19
	v_addc_co_u32_e64 v36, s[98:99], v36, v38, s[98:99]
	v_cmp_le_u32_e64 s[98:99], s8, v23
	v_addc_co_u32_e64 v36, s[100:101], v36, v40, s[100:101]
	v_cmp_le_u32_e64 s[100:101], s8, v28
	v_addc_co_u32_e32 v36, vcc, v36, v42, vcc
	v_cmp_le_u32_e32 vcc, s8, v30
	v_addc_co_u32_e64 v36, s[98:99], v36, v44, s[98:99]
	v_cmp_le_u32_e64 s[98:99], s8, v32
	v_addc_co_u32_e64 v36, s[100:101], v36, v46, s[100:101]
	v_cmp_le_u32_e64 s[100:101], s8, v33
	v_addc_co_u32_e32 v36, vcc, v36, v48, vcc
	v_cmp_le_u32_e32 vcc, s8, v4
	v_addc_co_u32_e64 v36, s[98:99], v36, v50, s[98:99]
	v_cmp_le_u32_e64 s[98:99], s8, v8
	v_addc_co_u32_e64 v35, s[100:101], v36, v35, s[100:101]
	v_cmp_le_u32_e64 s[100:101], s8, v12
	v_addc_co_u32_e32 v35, vcc, v35, v37, vcc
	v_cmp_le_u32_e32 vcc, s8, v16
	v_addc_co_u32_e64 v35, s[98:99], v35, v39, s[98:99]
	v_cmp_le_u32_e64 s[98:99], s8, v20
	v_addc_co_u32_e64 v35, s[100:101], v35, v41, s[100:101]
	v_cmp_le_u32_e64 s[100:101], s8, v24
	v_addc_co_u32_e32 v35, vcc, v35, v43, vcc
	v_cmp_le_u32_e32 vcc, s8, v27
	v_addc_co_u32_e64 v35, s[98:99], v35, v45, s[98:99]
	v_addc_co_u32_e64 v35, s[100:101], v35, v47, s[100:101]
	v_addc_co_u32_e32 v35, vcc, v35, v49, vcc
	s_nop 1
	v_add_u32_dpp v35, v35, v35 quad_perm:[1,0,3,2] row_mask:0xf bank_mask:0xf bound_ctrl:1
	s_nop 1
	v_add_u32_dpp v35, v35, v35 quad_perm:[2,3,0,1] row_mask:0xf bank_mask:0xf bound_ctrl:1
	s_nop 1
	v_add_u32_dpp v35, v35, v35 row_half_mirror row_mask:0xf bank_mask:0xf bound_ctrl:1
	s_nop 1
	v_add_u32_dpp v35, v35, v35 row_mirror row_mask:0xf bank_mask:0xf bound_ctrl:1
	s_nop 0
	v_readlane_b32 s2, v35, 0
	v_readlane_b32 s3, v35, 16
	s_add_i32 s2, s3, s2
	v_readlane_b32 s3, v35, 32
	s_add_i32 s10, s2, s3
	v_readlane_b32 s2, v35, 48
	s_add_i32 s10, s10, s2
	s_cmpk_lt_i32 s10, 0x100
	s_cbranch_scc0 .LBB0_1022
	s_cmp_eq_u32 s7, 0
	v_sub_u32_e64 v35, s7, 1 clamp
	s_cselect_b64 s[2:3], -1, 0
	v_readfirstlane_b32 s9, v35
	s_cbranch_execz .LBB0_1023

; DI int wave_isum(int v) {
;   v += __builtin_amdgcn_update_dpp(0, v, 0xB1, 0xf, 0xf, true);
;   v += __builtin_amdgcn_update_dpp(0, v, 0x4E, 0xf, 0xf, true);
;   v += __builtin_amdgcn_update_dpp(0, v, 0x141, 0xf, 0xf, true);
;   v += __builtin_amdgcn_update_dpp(0, v, 0x140, 0xf, 0xf, true);
;   return __builtin_amdgcn_readlane(v, 0) + __builtin_amdgcn_readlane(v, 16) + __builtin_amdgcn_readlane(v, 32) + __builtin_amdgcn_readlane(v, 48);
; template <int NJ>
; DI void b1_select(const float* sc, int nj, unsigned* mo) {
;     ...
; #pragma unroll 1
;     ...
;       const unsigned cand = T | (1u << bit);
;       int c0 = 0, c1 = 0;
; #pragma unroll
;       for (int j = 0; j < NJ; ++j) { if (j & 1) c1 += (key[j] >= cand) ? 1 : 0; else c0 += (key[j] >= cand) ? 1 : 0; }
;       const int cnt = wave_isum(c0 + c1);
;       if (cnt >= 256) { T = cand; if (cnt == 256) break; }
;     }
.LBB0_1026:
	s_lshl_b32 s0, 1, s6
	s_or_b32 s2, s97, s0
	v_cmp_le_u32_e32 vcc, s2, v2
	v_cmp_le_u32_e64 s[98:99], s2, v7
	v_cmp_le_u32_e64 s[100:101], s2, v3
	v_cndmask_b32_e64 v34, 0, 1, vcc
	v_cmp_le_u32_e32 vcc, s2, v9
	v_cndmask_b32_e64 v35, 0, 1, s[98:99]
	v_cmp_le_u32_e64 s[98:99], s2, v6
	v_cndmask_b32_e64 v36, 0, 1, s[100:101]
	v_cmp_le_u32_e64 s[100:101], s2, v13
	v_cndmask_b32_e64 v37, 0, 1, vcc
	v_cmp_le_u32_e32 vcc, s2, v10
	v_cndmask_b32_e64 v38, 0, 1, s[98:99]
	v_cmp_le_u32_e64 s[98:99], s2, v17
	v_cndmask_b32_e64 v39, 0, 1, s[100:101]
	v_cmp_le_u32_e64 s[100:101], s2, v14
	v_cndmask_b32_e64 v40, 0, 1, vcc
	v_cmp_le_u32_e32 vcc, s2, v21
	v_cndmask_b32_e64 v41, 0, 1, s[98:99]
	v_cmp_le_u32_e64 s[98:99], s2, v18
	v_cndmask_b32_e64 v42, 0, 1, s[100:101]
	v_cmp_le_u32_e64 s[100:101], s2, v26
	v_cndmask_b32_e64 v43, 0, 1, vcc
	v_cmp_le_u32_e32 vcc, s2, v22
	v_cndmask_b32_e64 v44, 0, 1, s[98:99]
	v_cmp_le_u32_e64 s[98:99], s2, v29
	v_cndmask_b32_e64 v45, 0, 1, s[100:101]
	v_cmp_le_u32_e64 s[100:101], s2, v25
	v_cndmask_b32_e64 v46, 0, 1, vcc
	v_cmp_le_u32_e32 vcc, s2, v31
	v_cndmask_b32_e64 v47, 0, 1, s[98:99]
	v_cmp_le_u32_e64 s[98:99], s2, v5
	v_cndmask_b32_e64 v48, 0, 1, s[100:101]
	v_cmp_le_u32_e64 s[100:101], s2, v11
	v_cndmask_b32_e64 v49, 0, 1, vcc
	v_cmp_le_u32_e32 vcc, s2, v15
	v_addc_co_u32_e64 v35, s[98:99], 0, v35, s[98:99]
	v_cmp_le_u32_e64 s[98:99], s2, v19
	v_addc_co_u32_e64 v35, s[100:101], v35, v37, s[100:101]
	v_cmp_le_u32_e64 s[100:101], s2, v23
	v_addc_co_u32_e32 v35, vcc, v35, v39, vcc
	v_cmp_le_u32_e32 vcc, s2, v28
	v_addc_co_u32_e64 v35, s[98:99], v35, v41, s[98:99]
	v_cmp_le_u32_e64 s[98:99], s2, v30
	v_addc_co_u32_e64 v35, s[100:101], v35, v43, s[100:101]
	v_cmp_le_u32_e64 s[100:101], s2, v32
	v_addc_co_u32_e32 v35, vcc, v35, v45, vcc
	v_cmp_le_u32_e32 vcc, s2, v33
	v_addc_co_u32_e64 v35, s[98:99], v35, v47, s[98:99]
	v_cmp_le_u32_e64 s[98:99], s2, v4
	v_addc_co_u32_e64 v35, s[100:101], v35, v49, s[100:101]
	v_cmp_le_u32_e64 s[100:101], s2, v8
	v_addc_co_u32_e32 v34, vcc, v35, v34, vcc
	v_cmp_le_u32_e32 vcc, s2, v12
	v_addc_co_u32_e64 v34, s[98:99], v34, v36, s[98:99]
	v_cmp_le_u32_e64 s[98:99], s2, v16
	v_addc_co_u32_e64 v34, s[100:101], v34, v38, s[100:101]
	v_cmp_le_u32_e64 s[100:101], s2, v20
	v_addc_co_u32_e32 v34, vcc, v34, v40, vcc
	v_cmp_le_u32_e32 vcc, s2, v24
	v_addc_co_u32_e64 v34, s[98:99], v34, v42, s[98:99]
	v_cmp_le_u32_e64 s[98:99], s2, v27
	v_addc_co_u32_e64 v34, s[100:101], v34, v44, s[100:101]
	v_addc_co_u32_e32 v34, vcc, v34, v46, vcc
	v_addc_co_u32_e64 v34, s[98:99], v34, v48, s[98:99]
	s_nop 1
	v_add_u32_dpp v34, v34, v34 quad_perm:[1,0,3,2] row_mask:0xf bank_mask:0xf bound_ctrl:1
	s_nop 1
	v_add_u32_dpp v34, v34, v34 quad_perm:[2,3,0,1] row_mask:0xf bank_mask:0xf bound_ctrl:1
	s_nop 1
	v_add_u32_dpp v34, v34, v34 row_half_mirror row_mask:0xf bank_mask:0xf bound_ctrl:1
	s_nop 1
	v_add_u32_dpp v34, v34, v34 row_mirror row_mask:0xf bank_mask:0xf bound_ctrl:1
	s_nop 0
	v_readlane_b32 s0, v34, 0
	v_readlane_b32 s1, v34, 16
	v_readlane_b32 s3, v34, 32
	s_add_i32 s0, s1, s0
	v_readlane_b32 s4, v34, 48
	s_add_i32 s0, s0, s3
	s_add_i32 s3, s0, s4
	s_cmpk_lg_i32 s3, 0x100
	s_cselect_b64 s[0:1], -1, 0
	s_cmpk_gt_i32 s3, 0xff
	s_cselect_b32 s97, s2, s97
	s_add_i32 s2, s6, -1
	s_cmp_gt_i32 s6, 0
	s_mov_b32 s6, s2
	s_cselect_b64 s[2:3], -1, 0
	s_and_b64 s[0:1], s[0:1], s[2:3]
	s_and_b64 vcc, exec, s[0:1]
	s_cbranch_vccnz .LBB0_1026

; DI int wave_isum(int v) {
;   v += __builtin_amdgcn_update_dpp(0, v, 0xB1, 0xf, 0xf, true);
;   v += __builtin_amdgcn_update_dpp(0, v, 0x4E, 0xf, 0xf, true);
;   v += __builtin_amdgcn_update_dpp(0, v, 0x141, 0xf, 0xf, true);
;   v += __builtin_amdgcn_update_dpp(0, v, 0x140, 0xf, 0xf, true);
;   return __builtin_amdgcn_readlane(v, 0) + __builtin_amdgcn_readlane(v, 16) + __builtin_amdgcn_readlane(v, 32) + __builtin_amdgcn_readlane(v, 48);
; template <int NJ>
; DI void b1_select(const float* sc, int nj, unsigned* mo) {
;     ...
;     unsigned E = M >> 23;
; #pragma unroll 1
;     for (int i = 0; i < 8; ++i) {
;       const unsigned cand = E << 23;
;       int c0 = 0, c1 = 0;
; #pragma unroll
;       for (int j = 0; j < NJ; ++j) { if (j & 1) c1 += (key[j] >= cand) ? 1 : 0; else c0 += (key[j] >= cand) ? 1 : 0; }
;       const int cnt = wave_isum(c0 + c1);
;       if (cnt >= 256) { T = cand; bit = 22; exact = (cnt == 256); break; }
;       if (E == 0u) break;
;       --E;
;     }
.LBB0_1092:
	s_lshl_b32 s8, s7, 23
	v_cmp_le_u32_e32 vcc, s8, v2
	s_mov_b64 s[4:5], -1
	s_nop 0
	v_cndmask_b32_e64 v35, 0, 1, vcc
	v_cmp_le_u32_e32 vcc, s8, v7
	v_cmp_le_u32_e64 s[98:99], s8, v3
	v_cmp_le_u32_e64 s[100:101], s8, v9
	v_cndmask_b32_e64 v36, 0, 1, vcc
	v_cmp_le_u32_e32 vcc, s8, v6
	v_cndmask_b32_e64 v37, 0, 1, s[98:99]
	v_cmp_le_u32_e64 s[98:99], s8, v13
	v_cndmask_b32_e64 v38, 0, 1, s[100:101]
	v_cmp_le_u32_e64 s[100:101], s8, v10
	v_cndmask_b32_e64 v39, 0, 1, vcc
	v_cmp_le_u32_e32 vcc, s8, v17
	v_cndmask_b32_e64 v40, 0, 1, s[98:99]
	v_cmp_le_u32_e64 s[98:99], s8, v14
	v_cndmask_b32_e64 v41, 0, 1, s[100:101]
	v_cmp_le_u32_e64 s[100:101], s8, v21
	v_cndmask_b32_e64 v42, 0, 1, vcc
	v_cmp_le_u32_e32 vcc, s8, v18
	v_cndmask_b32_e64 v43, 0, 1, s[98:99]
	v_cmp_le_u32_e64 s[98:99], s8, v26
	v_cndmask_b32_e64 v44, 0, 1, s[100:101]
	v_cmp_le_u32_e64 s[100:101], s8, v22
	v_cndmask_b32_e64 v45, 0, 1, vcc
	v_cmp_le_u32_e32 vcc, s8, v29
	v_cndmask_b32_e64 v46, 0, 1, s[98:99]
	v_cmp_le_u32_e64 s[98:99], s8, v25
	v_cndmask_b32_e64 v47, 0, 1, s[100:101]
	v_cmp_le_u32_e64 s[100:101], s8, v32
	v_cndmask_b32_e64 v48, 0, 1, vcc
	v_cmp_le_u32_e32 vcc, s8, v5
	v_cndmask_b32_e64 v49, 0, 1, s[98:99]
	v_cmp_le_u32_e64 s[98:99], s8, v11
	v_cndmask_b32_e64 v50, 0, 1, s[100:101]
	v_cmp_le_u32_e64 s[100:101], s8, v15
	v_addc_co_u32_e32 v36, vcc, 0, v36, vcc
	v_cmp_le_u32_e32 vcc, s8, v19
	v_addc_co_u32_e64 v36, s[98:99], v36, v38, s[98:99]
	v_cmp_le_u32_e64 s[98:99], s8, v23
	v_addc_co_u32_e64 v36, s[100:101], v36, v40, s[100:101]
	v_cmp_le_u32_e64 s[100:101], s8, v28
	v_addc_co_u32_e32 v36, vcc, v36, v42, vcc
	v_cmp_le_u32_e32 vcc, s8, v30
	v_addc_co_u32_e64 v36, s[98:99], v36, v44, s[98:99]
	v_cmp_le_u32_e64 s[98:99], s8, v31
	v_addc_co_u32_e64 v36, s[100:101], v36, v46, s[100:101]
	v_cmp_le_u32_e64 s[100:101], s8, v33
	v_addc_co_u32_e32 v36, vcc, v36, v48, vcc
	v_cmp_le_u32_e32 vcc, s8, v4
	v_addc_co_u32_e64 v36, s[98:99], v36, v50, s[98:99]
	v_cmp_le_u32_e64 s[98:99], s8, v8
	v_addc_co_u32_e64 v35, s[100:101], v36, v35, s[100:101]
	v_cmp_le_u32_e64 s[100:101], s8, v12
	v_addc_co_u32_e32 v35, vcc, v35, v37, vcc
	v_cmp_le_u32_e32 vcc, s8, v16
	v_addc_co_u32_e64 v35, s[98:99], v35, v39, s[98:99]
	v_cmp_le_u32_e64 s[98:99], s8, v20
	v_addc_co_u32_e64 v35, s[100:101], v35, v41, s[100:101]
	v_cmp_le_u32_e64 s[100:101], s8, v24
	v_addc_co_u32_e32 v35, vcc, v35, v43, vcc
	v_cmp_le_u32_e32 vcc, s8, v27
	v_addc_co_u32_e64 v35, s[98:99], v35, v45, s[98:99]
	v_addc_co_u32_e64 v35, s[100:101], v35, v47, s[100:101]
	v_addc_co_u32_e32 v35, vcc, v35, v49, vcc
	s_nop 1
	v_add_u32_dpp v35, v35, v35 quad_perm:[1,0,3,2] row_mask:0xf bank_mask:0xf bound_ctrl:1
	s_nop 1
	v_add_u32_dpp v35, v35, v35 quad_perm:[2,3,0,1] row_mask:0xf bank_mask:0xf bound_ctrl:1
	s_nop 1
	v_add_u32_dpp v35, v35, v35 row_half_mirror row_mask:0xf bank_mask:0xf bound_ctrl:1
	s_nop 1
	v_add_u32_dpp v35, v35, v35 row_mirror row_mask:0xf bank_mask:0xf bound_ctrl:1
	s_nop 0
	v_readlane_b32 s2, v35, 0
	v_readlane_b32 s3, v35, 16
	s_add_i32 s2, s3, s2
	v_readlane_b32 s3, v35, 32
	s_add_i32 s10, s2, s3
	v_readlane_b32 s2, v35, 48
	s_add_i32 s10, s10, s2
	s_cmpk_lt_i32 s10, 0x100
	s_cbranch_scc0 .LBB0_1095
	s_cmp_eq_u32 s7, 0
	v_sub_u32_e64 v35, s7, 1 clamp
	s_cselect_b64 s[2:3], -1, 0
	v_readfirstlane_b32 s9, v35
	s_cbranch_execz .LBB0_1096

; DI int wave_isum(int v) {
;   v += __builtin_amdgcn_update_dpp(0, v, 0xB1, 0xf, 0xf, true);
;   v += __builtin_amdgcn_update_dpp(0, v, 0x4E, 0xf, 0xf, true);
;   v += __builtin_amdgcn_update_dpp(0, v, 0x141, 0xf, 0xf, true);
;   v += __builtin_amdgcn_update_dpp(0, v, 0x140, 0xf, 0xf, true);
;   return __builtin_amdgcn_readlane(v, 0) + __builtin_amdgcn_readlane(v, 16) + __builtin_amdgcn_readlane(v, 32) + __builtin_amdgcn_readlane(v, 48);
; template <int NJ>
; DI void b1_select(const float* sc, int nj, unsigned* mo) {
;     ...
; #pragma unroll 1
;     ...
;       const unsigned cand = T | (1u << bit);
;       int c0 = 0, c1 = 0;
; #pragma unroll
;       for (int j = 0; j < NJ; ++j) { if (j & 1) c1 += (key[j] >= cand) ? 1 : 0; else c0 += (key[j] >= cand) ? 1 : 0; }
;       const int cnt = wave_isum(c0 + c1);
;       if (cnt >= 256) { T = cand; if (cnt == 256) break; }
;     }
.LBB0_1099:
	s_lshl_b32 s0, 1, s6
	s_or_b32 s2, s72, s0
	v_cmp_le_u32_e32 vcc, s2, v2
	v_cmp_le_u32_e64 s[98:99], s2, v7
	v_cmp_le_u32_e64 s[100:101], s2, v3
	v_cndmask_b32_e64 v34, 0, 1, vcc
	v_cmp_le_u32_e32 vcc, s2, v9
	v_cndmask_b32_e64 v35, 0, 1, s[98:99]
	v_cmp_le_u32_e64 s[98:99], s2, v6
	v_cndmask_b32_e64 v36, 0, 1, s[100:101]
	v_cmp_le_u32_e64 s[100:101], s2, v13
	v_cndmask_b32_e64 v37, 0, 1, vcc
	v_cmp_le_u32_e32 vcc, s2, v10
	v_cndmask_b32_e64 v38, 0, 1, s[98:99]
	v_cmp_le_u32_e64 s[98:99], s2, v17
	v_cndmask_b32_e64 v39, 0, 1, s[100:101]
	v_cmp_le_u32_e64 s[100:101], s2, v14
	v_cndmask_b32_e64 v40, 0, 1, vcc
	v_cmp_le_u32_e32 vcc, s2, v21
	v_cndmask_b32_e64 v41, 0, 1, s[98:99]
	v_cmp_le_u32_e64 s[98:99], s2, v18
	v_cndmask_b32_e64 v42, 0, 1, s[100:101]
	v_cmp_le_u32_e64 s[100:101], s2, v26
	v_cndmask_b32_e64 v43, 0, 1, vcc
	v_cmp_le_u32_e32 vcc, s2, v22
	v_cndmask_b32_e64 v44, 0, 1, s[98:99]
	v_cmp_le_u32_e64 s[98:99], s2, v29
	v_cndmask_b32_e64 v45, 0, 1, s[100:101]
	v_cmp_le_u32_e64 s[100:101], s2, v25
	v_cndmask_b32_e64 v46, 0, 1, vcc
	v_cmp_le_u32_e32 vcc, s2, v32
	v_cndmask_b32_e64 v47, 0, 1, s[98:99]
	v_cmp_le_u32_e64 s[98:99], s2, v5
	v_cndmask_b32_e64 v48, 0, 1, s[100:101]
	v_cmp_le_u32_e64 s[100:101], s2, v11
	v_cndmask_b32_e64 v49, 0, 1, vcc
	v_cmp_le_u32_e32 vcc, s2, v15
	v_addc_co_u32_e64 v35, s[98:99], 0, v35, s[98:99]
	v_cmp_le_u32_e64 s[98:99], s2, v19
	v_addc_co_u32_e64 v35, s[100:101], v35, v37, s[100:101]
	v_cmp_le_u32_e64 s[100:101], s2, v23
	v_addc_co_u32_e32 v35, vcc, v35, v39, vcc
	v_cmp_le_u32_e32 vcc, s2, v28
	v_addc_co_u32_e64 v35, s[98:99], v35, v41, s[98:99]
	v_cmp_le_u32_e64 s[98:99], s2, v30
	v_addc_co_u32_e64 v35, s[100:101], v35, v43, s[100:101]
	v_cmp_le_u32_e64 s[100:101], s2, v31
	v_addc_co_u32_e32 v35, vcc, v35, v45, vcc
	v_cmp_le_u32_e32 vcc, s2, v33
	v_addc_co_u32_e64 v35, s[98:99], v35, v47, s[98:99]
	v_cmp_le_u32_e64 s[98:99], s2, v4
	v_addc_co_u32_e64 v35, s[100:101], v35, v49, s[100:101]
	v_cmp_le_u32_e64 s[100:101], s2, v8
	v_addc_co_u32_e32 v34, vcc, v35, v34, vcc
	v_cmp_le_u32_e32 vcc, s2, v12
	v_addc_co_u32_e64 v34, s[98:99], v34, v36, s[98:99]
	v_cmp_le_u32_e64 s[98:99], s2, v16
	v_addc_co_u32_e64 v34, s[100:101], v34, v38, s[100:101]
	v_cmp_le_u32_e64 s[100:101], s2, v20
	v_addc_co_u32_e32 v34, vcc, v34, v40, vcc
	v_cmp_le_u32_e32 vcc, s2, v24
	v_addc_co_u32_e64 v34, s[98:99], v34, v42, s[98:99]
	v_cmp_le_u32_e64 s[98:99], s2, v27
	v_addc_co_u32_e64 v34, s[100:101], v34, v44, s[100:101]
	v_addc_co_u32_e32 v34, vcc, v34, v46, vcc
	v_addc_co_u32_e64 v34, s[98:99], v34, v48, s[98:99]
	s_nop 1
	v_add_u32_dpp v34, v34, v34 quad_perm:[1,0,3,2] row_mask:0xf bank_mask:0xf bound_ctrl:1
	s_nop 1
	v_add_u32_dpp v34, v34, v34 quad_perm:[2,3,0,1] row_mask:0xf bank_mask:0xf bound_ctrl:1
	s_nop 1
	v_add_u32_dpp v34, v34, v34 row_half_mirror row_mask:0xf bank_mask:0xf bound_ctrl:1
	s_nop 1
	v_add_u32_dpp v34, v34, v34 row_mirror row_mask:0xf bank_mask:0xf bound_ctrl:1
	s_nop 0
	v_readlane_b32 s0, v34, 0
	v_readlane_b32 s1, v34, 16
	v_readlane_b32 s3, v34, 32
	s_add_i32 s0, s1, s0
	v_readlane_b32 s4, v34, 48
	s_add_i32 s0, s0, s3
	s_add_i32 s3, s0, s4
	s_cmpk_lg_i32 s3, 0x100
	s_cselect_b64 s[0:1], -1, 0
	s_cmpk_gt_i32 s3, 0xff
	s_cselect_b32 s72, s2, s72
	s_add_i32 s2, s6, -1
	s_cmp_gt_i32 s6, 0
	s_mov_b32 s6, s2
	s_cselect_b64 s[2:3], -1, 0
	s_and_b64 s[0:1], s[0:1], s[2:3]
	s_and_b64 vcc, exec, s[0:1]
	s_cbranch_vccnz .LBB0_1099

; DI int wave_isum(int v) {
;   v += __builtin_amdgcn_update_dpp(0, v, 0xB1, 0xf, 0xf, true);
;   v += __builtin_amdgcn_update_dpp(0, v, 0x4E, 0xf, 0xf, true);
;   v += __builtin_amdgcn_update_dpp(0, v, 0x141, 0xf, 0xf, true);
;   v += __builtin_amdgcn_update_dpp(0, v, 0x140, 0xf, 0xf, true);
;   return __builtin_amdgcn_readlane(v, 0) + __builtin_amdgcn_readlane(v, 16) + __builtin_amdgcn_readlane(v, 32) + __builtin_amdgcn_readlane(v, 48);
; template <int NJ>
; DI void b1_select(const float* sc, int nj, unsigned* mo) {
;     ...
;     unsigned E = M >> 23;
; #pragma unroll 1
;     for (int i = 0; i < 8; ++i) {
;       const unsigned cand = E << 23;
;       int c0 = 0, c1 = 0;
; #pragma unroll
;       for (int j = 0; j < NJ; ++j) { if (j & 1) c1 += (key[j] >= cand) ? 1 : 0; else c0 += (key[j] >= cand) ? 1 : 0; }
;       const int cnt = wave_isum(c0 + c1);
;       if (cnt >= 256) { T = cand; bit = 22; exact = (cnt == 256); break; }
;       if (E == 0u) break;
;       --E;
;     }
.LBB0_1119:
	s_lshl_b32 s8, s7, 23
	v_cmp_le_u32_e32 vcc, s8, v2
	s_mov_b64 s[4:5], -1
	s_nop 0
	v_cndmask_b32_e64 v11, 0, 1, vcc
	v_cmp_le_u32_e32 vcc, s8, v6
	v_cmp_le_u32_e64 s[98:99], s8, v3
	v_cmp_le_u32_e64 s[100:101], s8, v7
	v_cndmask_b32_e64 v12, 0, 1, vcc
	v_cmp_le_u32_e32 vcc, s8, v5
	v_cndmask_b32_e64 v13, 0, 1, s[98:99]
	v_cmp_le_u32_e64 s[98:99], s8, v8
	v_cndmask_b32_e64 v14, 0, 1, s[100:101]
	v_cmp_le_u32_e64 s[100:101], s8, v9
	v_addc_co_u32_e32 v12, vcc, 0, v12, vcc
	v_cmp_le_u32_e32 vcc, s8, v4
	v_addc_co_u32_e64 v12, s[98:99], v12, v14, s[98:99]
	v_addc_co_u32_e64 v11, s[100:101], v12, v11, s[100:101]
	v_addc_co_u32_e32 v11, vcc, v11, v13, vcc
	s_nop 1
	v_add_u32_dpp v11, v11, v11 quad_perm:[1,0,3,2] row_mask:0xf bank_mask:0xf bound_ctrl:1
	s_nop 1
	v_add_u32_dpp v11, v11, v11 quad_perm:[2,3,0,1] row_mask:0xf bank_mask:0xf bound_ctrl:1
	s_nop 1
	v_add_u32_dpp v11, v11, v11 row_half_mirror row_mask:0xf bank_mask:0xf bound_ctrl:1
	s_nop 1
	v_add_u32_dpp v11, v11, v11 row_mirror row_mask:0xf bank_mask:0xf bound_ctrl:1
	s_nop 0
	v_readlane_b32 s2, v11, 0
	v_readlane_b32 s3, v11, 16
	s_add_i32 s2, s3, s2
	v_readlane_b32 s3, v11, 32
	s_add_i32 s10, s2, s3
	v_readlane_b32 s2, v11, 48
	s_add_i32 s10, s10, s2
	s_cmpk_lt_i32 s10, 0x100
	s_cbranch_scc0 .LBB0_1122
	s_cmp_eq_u32 s7, 0
	v_sub_u32_e64 v11, s7, 1 clamp
	s_cselect_b64 s[2:3], -1, 0
	v_readfirstlane_b32 s9, v11
	s_cbranch_execz .LBB0_1123

; DI int wave_isum(int v) {
;   v += __builtin_amdgcn_update_dpp(0, v, 0xB1, 0xf, 0xf, true);
;   v += __builtin_amdgcn_update_dpp(0, v, 0x4E, 0xf, 0xf, true);
;   v += __builtin_amdgcn_update_dpp(0, v, 0x141, 0xf, 0xf, true);
;   v += __builtin_amdgcn_update_dpp(0, v, 0x140, 0xf, 0xf, true);
;   return __builtin_amdgcn_readlane(v, 0) + __builtin_amdgcn_readlane(v, 16) + __builtin_amdgcn_readlane(v, 32) + __builtin_amdgcn_readlane(v, 48);
; template <int NJ>
; DI void b1_select(const float* sc, int nj, unsigned* mo) {
;     ...
; #pragma unroll 1
;     ...
;       const unsigned cand = T | (1u << bit);
;       int c0 = 0, c1 = 0;
; #pragma unroll
;       for (int j = 0; j < NJ; ++j) { if (j & 1) c1 += (key[j] >= cand) ? 1 : 0; else c0 += (key[j] >= cand) ? 1 : 0; }
;       const int cnt = wave_isum(c0 + c1);
;       if (cnt >= 256) { T = cand; if (cnt == 256) break; }
;     }
.LBB0_1126:
	s_lshl_b32 s0, 1, s6
	s_or_b32 s2, s30, s0
	v_cmp_le_u32_e32 vcc, s2, v2
	v_cmp_le_u32_e64 s[98:99], s2, v6
	v_cmp_le_u32_e64 s[100:101], s2, v3
	v_cndmask_b32_e64 v10, 0, 1, vcc
	v_cmp_le_u32_e32 vcc, s2, v7
	v_cndmask_b32_e64 v11, 0, 1, s[98:99]
	v_cmp_le_u32_e64 s[98:99], s2, v5
	v_cndmask_b32_e64 v12, 0, 1, s[100:101]
	v_cmp_le_u32_e64 s[100:101], s2, v8
	v_cndmask_b32_e64 v13, 0, 1, vcc
	v_cmp_le_u32_e32 vcc, s2, v9
	v_addc_co_u32_e64 v11, s[98:99], 0, v11, s[98:99]
	v_cmp_le_u32_e64 s[98:99], s2, v4
	v_addc_co_u32_e64 v11, s[100:101], v11, v13, s[100:101]
	v_addc_co_u32_e32 v10, vcc, v11, v10, vcc
	v_addc_co_u32_e64 v10, s[98:99], v10, v12, s[98:99]
	s_nop 1
	v_add_u32_dpp v10, v10, v10 quad_perm:[1,0,3,2] row_mask:0xf bank_mask:0xf bound_ctrl:1
	s_nop 1
	v_add_u32_dpp v10, v10, v10 quad_perm:[2,3,0,1] row_mask:0xf bank_mask:0xf bound_ctrl:1
	s_nop 1
	v_add_u32_dpp v10, v10, v10 row_half_mirror row_mask:0xf bank_mask:0xf bound_ctrl:1
	s_nop 1
	v_add_u32_dpp v10, v10, v10 row_mirror row_mask:0xf bank_mask:0xf bound_ctrl:1
	s_nop 0
	v_readlane_b32 s0, v10, 0
	v_readlane_b32 s1, v10, 16
	v_readlane_b32 s3, v10, 32
	s_add_i32 s0, s1, s0
	v_readlane_b32 s4, v10, 48
	s_add_i32 s0, s0, s3
	s_add_i32 s3, s0, s4
	s_cmpk_lg_i32 s3, 0x100
	s_cselect_b64 s[0:1], -1, 0
	s_cmpk_gt_i32 s3, 0xff
	s_cselect_b32 s30, s2, s30
	s_add_i32 s2, s6, -1
	s_cmp_gt_i32 s6, 0
	s_mov_b32 s6, s2
	s_cselect_b64 s[2:3], -1, 0
	s_and_b64 s[0:1], s[0:1], s[2:3]
	s_and_b64 vcc, exec, s[0:1]
	s_cbranch_vccnz .LBB0_1126

; DI int wave_isum(int v) {
;   v += __builtin_amdgcn_update_dpp(0, v, 0xB1, 0xf, 0xf, true);
;   v += __builtin_amdgcn_update_dpp(0, v, 0x4E, 0xf, 0xf, true);
;   v += __builtin_amdgcn_update_dpp(0, v, 0x141, 0xf, 0xf, true);
;   v += __builtin_amdgcn_update_dpp(0, v, 0x140, 0xf, 0xf, true);
;   return __builtin_amdgcn_readlane(v, 0) + __builtin_amdgcn_readlane(v, 16) + __builtin_amdgcn_readlane(v, 32) + __builtin_amdgcn_readlane(v, 48);
; template <int NJ>
; DI void b1_select(const float* sc, int nj, unsigned* mo) {
;     ...
; #pragma unroll 1
;     ...
;       const unsigned cand = T | (1u << bit);
;       int c0 = 0, c1 = 0;
; #pragma unroll
;       for (int j = 0; j < NJ; ++j) { if (j & 1) c1 += (key[j] >= cand) ? 1 : 0; else c0 += (key[j] >= cand) ? 1 : 0; }
;       const int cnt = wave_isum(c0 + c1);
;       if (cnt >= 256) { T = cand; if (cnt == 256) break; }
;     }
.LBB0_1151:
	s_lshl_b32 s0, 1, s6
	s_or_b32 s2, s18, s0
	v_cmp_le_u32_e32 vcc, s2, v2
	v_cmp_le_u32_e64 s[98:99], s2, v6
	v_cmp_le_u32_e64 s[100:101], s2, v3
	v_cndmask_b32_e64 v10, 0, 1, vcc
	v_cmp_le_u32_e32 vcc, s2, v7
	v_cndmask_b32_e64 v11, 0, 1, s[98:99]
	v_cmp_le_u32_e64 s[98:99], s2, v5
	v_cndmask_b32_e64 v12, 0, 1, s[100:101]
	v_cmp_le_u32_e64 s[100:101], s2, v8
	v_cndmask_b32_e64 v13, 0, 1, vcc
	v_cmp_le_u32_e32 vcc, s2, v9
	v_addc_co_u32_e64 v11, s[98:99], 0, v11, s[98:99]
	v_cmp_le_u32_e64 s[98:99], s2, v4
	v_addc_co_u32_e64 v11, s[100:101], v11, v13, s[100:101]
	v_addc_co_u32_e32 v10, vcc, v11, v10, vcc
	v_addc_co_u32_e64 v10, s[98:99], v10, v12, s[98:99]
	s_nop 1
	v_add_u32_dpp v10, v10, v10 quad_perm:[1,0,3,2] row_mask:0xf bank_mask:0xf bound_ctrl:1
	s_nop 1
	v_add_u32_dpp v10, v10, v10 quad_perm:[2,3,0,1] row_mask:0xf bank_mask:0xf bound_ctrl:1
	s_nop 1
	v_add_u32_dpp v10, v10, v10 row_half_mirror row_mask:0xf bank_mask:0xf bound_ctrl:1
	s_nop 1
	v_add_u32_dpp v10, v10, v10 row_mirror row_mask:0xf bank_mask:0xf bound_ctrl:1
	s_nop 0
	v_readlane_b32 s0, v10, 0
	v_readlane_b32 s1, v10, 16
	v_readlane_b32 s3, v10, 32
	s_add_i32 s0, s1, s0
	v_readlane_b32 s4, v10, 48
	s_add_i32 s0, s0, s3
	s_add_i32 s3, s0, s4
	s_cmpk_lg_i32 s3, 0x100
	s_cselect_b64 s[0:1], -1, 0
	s_cmpk_gt_i32 s3, 0xff
	s_cselect_b32 s18, s2, s18
	s_add_i32 s2, s6, -1
	s_cmp_gt_i32 s6, 0
	s_mov_b32 s6, s2
	s_cselect_b64 s[2:3], -1, 0
	s_and_b64 s[0:1], s[0:1], s[2:3]
	s_and_b64 vcc, exec, s[0:1]
	s_cbranch_vccnz .LBB0_1151

; DI int wave_isum(int v) {
;   v += __builtin_amdgcn_update_dpp(0, v, 0xB1, 0xf, 0xf, true);
;   v += __builtin_amdgcn_update_dpp(0, v, 0x4E, 0xf, 0xf, true);
;   v += __builtin_amdgcn_update_dpp(0, v, 0x141, 0xf, 0xf, true);
;   v += __builtin_amdgcn_update_dpp(0, v, 0x140, 0xf, 0xf, true);
;   return __builtin_amdgcn_readlane(v, 0) + __builtin_amdgcn_readlane(v, 16) + __builtin_amdgcn_readlane(v, 32) + __builtin_amdgcn_readlane(v, 48);
; template <int NJ>
; DI void b1_select(const float* sc, int nj, unsigned* mo) {
;     ...
;     unsigned E = M >> 23;
; #pragma unroll 1
;     for (int i = 0; i < 8; ++i) {
;       const unsigned cand = E << 23;
;       int c0 = 0, c1 = 0;
; #pragma unroll
;       for (int j = 0; j < NJ; ++j) { if (j & 1) c1 += (key[j] >= cand) ? 1 : 0; else c0 += (key[j] >= cand) ? 1 : 0; }
;       const int cnt = wave_isum(c0 + c1);
;       if (cnt >= 256) { T = cand; bit = 22; exact = (cnt == 256); break; }
;       if (E == 0u) break;
;       --E;
;     }
.LBB0_1166:
	s_lshl_b32 s9, s8, 23
	v_cmp_le_u32_e32 vcc, s9, v8
	s_mov_b64 s[4:5], -1
	s_nop 0
	v_cndmask_b32_e64 v68, 0, 1, vcc
	v_cmp_le_u32_e32 vcc, s9, v5
	v_cmp_le_u32_e64 s[98:99], s9, v3
	v_cmp_le_u32_e64 s[100:101], s9, v22
	v_cndmask_b32_e64 v69, 0, 1, vcc
	v_cmp_le_u32_e32 vcc, s9, v16
	v_cndmask_b32_e64 v70, 0, 1, s[98:99]
	v_cmp_le_u32_e64 s[98:99], s9, v13
	v_cndmask_b32_e64 v71, 0, 1, s[100:101]
	v_cmp_le_u32_e64 s[100:101], s9, v9
	v_cndmask_b32_e64 v72, 0, 1, vcc
	v_cmp_le_u32_e32 vcc, s9, v34
	v_cndmask_b32_e64 v73, 0, 1, s[98:99]
	v_cmp_le_u32_e64 s[98:99], s9, v28
	v_cndmask_b32_e64 v74, 0, 1, s[100:101]
	v_cmp_le_u32_e64 s[100:101], s9, v23
	v_cndmask_b32_e64 v75, 0, 1, vcc
	v_cmp_le_u32_e32 vcc, s9, v17
	v_cndmask_b32_e64 v76, 0, 1, s[98:99]
	v_cmp_le_u32_e64 s[98:99], s9, v42
	v_cndmask_b32_e64 v77, 0, 1, s[100:101]
	v_cmp_le_u32_e64 s[100:101], s9, v37
	v_cndmask_b32_e64 v78, 0, 1, vcc
	v_cmp_le_u32_e32 vcc, s9, v26
	v_cndmask_b32_e64 v79, 0, 1, s[98:99]
	v_cmp_le_u32_e64 s[98:99], s9, v18
	v_cndmask_b32_e64 v80, 0, 1, s[100:101]
	v_cmp_le_u32_e64 s[100:101], s9, v41
	v_cndmask_b32_e64 v81, 0, 1, vcc
	v_cmp_le_u32_e32 vcc, s9, v36
	v_cndmask_b32_e64 v82, 0, 1, s[98:99]
	v_cmp_le_u32_e64 s[98:99], s9, v35
	v_cndmask_b32_e64 v83, 0, 1, s[100:101]
	v_cmp_le_u32_e64 s[100:101], s9, v30
	v_cndmask_b32_e64 v84, 0, 1, vcc
	v_cmp_le_u32_e32 vcc, s9, v51
	v_cndmask_b32_e64 v85, 0, 1, s[98:99]
	v_cmp_le_u32_e64 s[98:99], s9, v47
	v_cndmask_b32_e64 v86, 0, 1, s[100:101]
	v_cmp_le_u32_e64 s[100:101], s9, v45
	v_cndmask_b32_e64 v87, 0, 1, vcc
	v_cmp_le_u32_e32 vcc, s9, v39
	v_cndmask_b32_e64 v88, 0, 1, s[98:99]
	v_cmp_le_u32_e64 s[98:99], s9, v59
	v_cndmask_b32_e64 v89, 0, 1, s[100:101]
	v_cmp_le_u32_e64 s[100:101], s9, v54
	v_cndmask_b32_e64 v90, 0, 1, vcc
	v_cmp_le_u32_e32 vcc, s9, v52
	v_cndmask_b32_e64 v91, 0, 1, s[98:99]
	v_cmp_le_u32_e64 s[98:99], s9, v48
	v_cndmask_b32_e64 v92, 0, 1, s[100:101]
	v_cmp_le_u32_e64 s[100:101], s9, v63
	v_cndmask_b32_e64 v93, 0, 1, vcc
	v_cmp_le_u32_e32 vcc, s9, v62
	v_cndmask_b32_e64 v94, 0, 1, s[98:99]
	v_cmp_le_u32_e64 s[98:99], s9, v60
	v_cndmask_b32_e64 v95, 0, 1, s[100:101]
	v_cmp_le_u32_e64 s[100:101], s9, v56
	v_cndmask_b32_e64 v96, 0, 1, vcc
	v_cmp_le_u32_e32 vcc, s9, v66
	v_cndmask_b32_e64 v97, 0, 1, s[98:99]
	v_cmp_le_u32_e64 s[98:99], s9, v64
	v_cndmask_b32_e64 v98, 0, 1, s[100:101]
	v_cmp_le_u32_e64 s[100:101], s9, v2
	v_cndmask_b32_e64 v99, 0, 1, vcc
	v_cmp_le_u32_e32 vcc, s9, v10
	v_cndmask_b32_e64 v102, 0, 1, s[98:99]
	v_cmp_le_u32_e64 s[98:99], s9, v7
	v_addc_co_u32_e64 v69, s[100:101], v69, v70, s[100:101]
	v_cmp_le_u32_e64 s[100:101], s9, v19
	v_addc_co_u32_e32 v69, vcc, v69, v72, vcc
	v_cmp_le_u32_e32 vcc, s9, v15
	v_addc_co_u32_e64 v69, s[98:99], v69, v74, s[98:99]
	v_cmp_le_u32_e64 s[98:99], s9, v24
	v_addc_co_u32_e64 v69, s[100:101], v69, v76, s[100:101]
	v_cmp_le_u32_e64 s[100:101], s9, v12
	v_addc_co_u32_e32 v69, vcc, v69, v78, vcc
	v_cmp_le_u32_e32 vcc, s9, v29
	v_addc_co_u32_e64 v69, s[98:99], v69, v80, s[98:99]
	v_cmp_le_u32_e64 s[98:99], s9, v27
	v_addc_co_u32_e64 v69, s[100:101], v69, v82, s[100:101]
	v_cmp_le_u32_e64 s[100:101], s9, v40
	v_addc_co_u32_e32 v69, vcc, v69, v84, vcc
	v_cmp_le_u32_e32 vcc, s9, v38
	v_addc_co_u32_e64 v69, s[98:99], v69, v86, s[98:99]
	v_cmp_le_u32_e64 s[98:99], s9, v49
	v_addc_co_u32_e64 v69, s[100:101], v69, v88, s[100:101]
	v_cmp_le_u32_e64 s[100:101], s9, v46
	v_addc_co_u32_e32 v69, vcc, v69, v90, vcc
	v_cmp_le_u32_e32 vcc, s9, v57
	v_addc_co_u32_e64 v69, s[98:99], v69, v92, s[98:99]
	v_cmp_le_u32_e64 s[98:99], s9, v55
	v_addc_co_u32_e64 v69, s[100:101], v69, v94, s[100:101]
	v_cmp_le_u32_e64 s[100:101], s9, v6
	v_addc_co_u32_e32 v69, vcc, v69, v96, vcc
	v_cmp_le_u32_e32 vcc, s9, v4
	v_addc_co_u32_e64 v69, s[98:99], v69, v98, s[98:99]
	v_cmp_le_u32_e64 s[98:99], s9, v14
	v_addc_co_u32_e64 v69, s[100:101], v69, v102, s[100:101]
	v_cmp_le_u32_e64 s[100:101], s9, v11
	v_addc_co_u32_e32 v68, vcc, v69, v68, vcc
	v_cmp_le_u32_e32 vcc, s9, v25
	v_addc_co_u32_e64 v68, s[98:99], v68, v71, s[98:99]
	v_cmp_le_u32_e64 s[98:99], s9, v21
	v_addc_co_u32_e64 v68, s[100:101], v68, v73, s[100:101]
	v_cmp_le_u32_e64 s[100:101], s9, v31
	v_addc_co_u32_e32 v68, vcc, v68, v75, vcc
	v_cmp_le_u32_e32 vcc, s9, v20
	v_addc_co_u32_e64 v68, s[98:99], v68, v77, s[98:99]
	v_cmp_le_u32_e64 s[98:99], s9, v32
	v_addc_co_u32_e64 v68, s[100:101], v68, v79, s[100:101]
	v_cmp_le_u32_e64 s[100:101], s9, v33
	v_addc_co_u32_e32 v68, vcc, v68, v81, vcc
	v_cmp_le_u32_e32 vcc, s9, v44
	v_addc_co_u32_e64 v68, s[98:99], v68, v83, s[98:99]
	v_cmp_le_u32_e64 s[98:99], s9, v43
	v_addc_co_u32_e64 v68, s[100:101], v68, v85, s[100:101]
	v_cmp_le_u32_e64 s[100:101], s9, v53
	v_addc_co_u32_e32 v68, vcc, v68, v87, vcc
	v_cmp_le_u32_e32 vcc, s9, v50
	v_addc_co_u32_e64 v68, s[98:99], v68, v89, s[98:99]
	v_cmp_le_u32_e64 s[98:99], s9, v61
	v_addc_co_u32_e64 v68, s[100:101], v68, v91, s[100:101]
	v_cmp_le_u32_e64 s[100:101], s9, v58
	v_addc_co_u32_e32 v68, vcc, v68, v93, vcc
	v_cmp_le_u32_e32 vcc, s9, v65
	v_addc_co_u32_e64 v68, s[98:99], v68, v95, s[98:99]
	v_addc_co_u32_e64 v68, s[100:101], v68, v97, s[100:101]
	v_addc_co_u32_e32 v68, vcc, v68, v99, vcc
	s_nop 1
	v_add_u32_dpp v68, v68, v68 quad_perm:[1,0,3,2] row_mask:0xf bank_mask:0xf bound_ctrl:1
	s_nop 1
	v_add_u32_dpp v68, v68, v68 quad_perm:[2,3,0,1] row_mask:0xf bank_mask:0xf bound_ctrl:1
	s_nop 1
	v_add_u32_dpp v68, v68, v68 row_half_mirror row_mask:0xf bank_mask:0xf bound_ctrl:1
	s_nop 1
	v_add_u32_dpp v68, v68, v68 row_mirror row_mask:0xf bank_mask:0xf bound_ctrl:1
	s_nop 0
	v_readlane_b32 s2, v68, 0
	v_readlane_b32 s3, v68, 16
	s_add_i32 s2, s3, s2
	v_readlane_b32 s3, v68, 32
	s_add_i32 s11, s2, s3
	v_readlane_b32 s2, v68, 48
	s_add_i32 s11, s11, s2
	s_cmpk_lt_i32 s11, 0x100
	s_cbranch_scc0 .LBB0_1169
	s_cmp_eq_u32 s8, 0
	v_sub_u32_e64 v68, s8, 1 clamp
	s_cselect_b64 s[2:3], -1, 0
	v_readfirstlane_b32 s10, v68
	s_cbranch_execz .LBB0_1170

; DI int wave_isum(int v) {
;   v += __builtin_amdgcn_update_dpp(0, v, 0xB1, 0xf, 0xf, true);
;   v += __builtin_amdgcn_update_dpp(0, v, 0x4E, 0xf, 0xf, true);
;   v += __builtin_amdgcn_update_dpp(0, v, 0x141, 0xf, 0xf, true);
;   v += __builtin_amdgcn_update_dpp(0, v, 0x140, 0xf, 0xf, true);
;   return __builtin_amdgcn_readlane(v, 0) + __builtin_amdgcn_readlane(v, 16) + __builtin_amdgcn_readlane(v, 32) + __builtin_amdgcn_readlane(v, 48);
; template <int NJ>
; DI void b1_select(const float* sc, int nj, unsigned* mo) {
;     ...
; #pragma unroll 1
;     ...
;       const unsigned cand = T | (1u << bit);
;       int c0 = 0, c1 = 0;
; #pragma unroll
;       for (int j = 0; j < NJ; ++j) { if (j & 1) c1 += (key[j] >= cand) ? 1 : 0; else c0 += (key[j] >= cand) ? 1 : 0; }
;       const int cnt = wave_isum(c0 + c1);
;       if (cnt >= 256) { T = cand; if (cnt == 256) break; }
;     }
.LBB0_1173:
	s_lshl_b32 s0, 1, s7
	s_or_b32 s0, s97, s0
	v_cmp_le_u32_e32 vcc, s0, v8
	v_cmp_le_u32_e64 s[98:99], s0, v5
	v_cmp_le_u32_e64 s[100:101], s0, v3
	v_cndmask_b32_e64 v67, 0, 1, vcc
	v_cmp_le_u32_e32 vcc, s0, v22
	v_cndmask_b32_e64 v68, 0, 1, s[98:99]
	v_cmp_le_u32_e64 s[98:99], s0, v16
	v_cndmask_b32_e64 v69, 0, 1, s[100:101]
	v_cmp_le_u32_e64 s[100:101], s0, v13
	v_cndmask_b32_e64 v70, 0, 1, vcc
	v_cmp_le_u32_e32 vcc, s0, v9
	v_cndmask_b32_e64 v71, 0, 1, s[98:99]
	v_cmp_le_u32_e64 s[98:99], s0, v34
	v_cndmask_b32_e64 v72, 0, 1, s[100:101]
	v_cmp_le_u32_e64 s[100:101], s0, v28
	v_cndmask_b32_e64 v73, 0, 1, vcc
	v_cmp_le_u32_e32 vcc, s0, v23
	v_cndmask_b32_e64 v74, 0, 1, s[98:99]
	v_cmp_le_u32_e64 s[98:99], s0, v17
	v_cndmask_b32_e64 v75, 0, 1, s[100:101]
	v_cmp_le_u32_e64 s[100:101], s0, v42
	v_cndmask_b32_e64 v76, 0, 1, vcc
	v_cmp_le_u32_e32 vcc, s0, v37
	v_cndmask_b32_e64 v77, 0, 1, s[98:99]
	v_cmp_le_u32_e64 s[98:99], s0, v26
	v_cndmask_b32_e64 v78, 0, 1, s[100:101]
	v_cmp_le_u32_e64 s[100:101], s0, v18
	v_cndmask_b32_e64 v79, 0, 1, vcc
	v_cmp_le_u32_e32 vcc, s0, v41
	v_cndmask_b32_e64 v80, 0, 1, s[98:99]
	v_cmp_le_u32_e64 s[98:99], s0, v36
	v_cndmask_b32_e64 v81, 0, 1, s[100:101]
	v_cmp_le_u32_e64 s[100:101], s0, v35
	v_cndmask_b32_e64 v82, 0, 1, vcc
	v_cmp_le_u32_e32 vcc, s0, v30
	v_cndmask_b32_e64 v83, 0, 1, s[98:99]
	v_cmp_le_u32_e64 s[98:99], s0, v51
	v_cndmask_b32_e64 v84, 0, 1, s[100:101]
	v_cmp_le_u32_e64 s[100:101], s0, v47
	v_cndmask_b32_e64 v85, 0, 1, vcc
	v_cmp_le_u32_e32 vcc, s0, v45
	v_cndmask_b32_e64 v86, 0, 1, s[98:99]
	v_cmp_le_u32_e64 s[98:99], s0, v39
	v_cndmask_b32_e64 v87, 0, 1, s[100:101]
	v_cmp_le_u32_e64 s[100:101], s0, v59
	v_cndmask_b32_e64 v88, 0, 1, vcc
	v_cmp_le_u32_e32 vcc, s0, v54
	v_cndmask_b32_e64 v89, 0, 1, s[98:99]
	v_cmp_le_u32_e64 s[98:99], s0, v52
	v_cndmask_b32_e64 v90, 0, 1, s[100:101]
	v_cmp_le_u32_e64 s[100:101], s0, v48
	v_cndmask_b32_e64 v91, 0, 1, vcc
	v_cmp_le_u32_e32 vcc, s0, v63
	v_cndmask_b32_e64 v92, 0, 1, s[98:99]
	v_cmp_le_u32_e64 s[98:99], s0, v62
	v_cndmask_b32_e64 v93, 0, 1, s[100:101]
	v_cmp_le_u32_e64 s[100:101], s0, v60
	v_cndmask_b32_e64 v94, 0, 1, vcc
	v_cmp_le_u32_e32 vcc, s0, v56
	v_cndmask_b32_e64 v95, 0, 1, s[98:99]
	v_cmp_le_u32_e64 s[98:99], s0, v66
	v_cndmask_b32_e64 v96, 0, 1, s[100:101]
	v_cmp_le_u32_e64 s[100:101], s0, v64
	v_cndmask_b32_e64 v97, 0, 1, vcc
	v_cmp_le_u32_e32 vcc, s0, v2
	v_cndmask_b32_e64 v98, 0, 1, s[98:99]
	v_cmp_le_u32_e64 s[98:99], s0, v10
	v_cndmask_b32_e64 v99, 0, 1, s[100:101]
	v_cmp_le_u32_e64 s[100:101], s0, v7
	v_addc_co_u32_e32 v68, vcc, v68, v69, vcc
	v_cmp_le_u32_e32 vcc, s0, v19
	v_addc_co_u32_e64 v68, s[98:99], v68, v71, s[98:99]
	v_cmp_le_u32_e64 s[98:99], s0, v15
	v_addc_co_u32_e64 v68, s[100:101], v68, v73, s[100:101]
	v_cmp_le_u32_e64 s[100:101], s0, v24
	v_addc_co_u32_e32 v68, vcc, v68, v75, vcc
	v_cmp_le_u32_e32 vcc, s0, v12
	v_addc_co_u32_e64 v68, s[98:99], v68, v77, s[98:99]
	v_cmp_le_u32_e64 s[98:99], s0, v29
	v_addc_co_u32_e64 v68, s[100:101], v68, v79, s[100:101]
	v_cmp_le_u32_e64 s[100:101], s0, v27
	v_addc_co_u32_e32 v68, vcc, v68, v81, vcc
	v_cmp_le_u32_e32 vcc, s0, v40
	v_addc_co_u32_e64 v68, s[98:99], v68, v83, s[98:99]
	v_cmp_le_u32_e64 s[98:99], s0, v38
	v_addc_co_u32_e64 v68, s[100:101], v68, v85, s[100:101]
	v_cmp_le_u32_e64 s[100:101], s0, v49
	v_addc_co_u32_e32 v68, vcc, v68, v87, vcc
	v_cmp_le_u32_e32 vcc, s0, v46
	v_addc_co_u32_e64 v68, s[98:99], v68, v89, s[98:99]
	v_cmp_le_u32_e64 s[98:99], s0, v57
	v_addc_co_u32_e64 v68, s[100:101], v68, v91, s[100:101]
	v_cmp_le_u32_e64 s[100:101], s0, v55
	v_addc_co_u32_e32 v68, vcc, v68, v93, vcc
	v_cmp_le_u32_e32 vcc, s0, v6
	v_addc_co_u32_e64 v68, s[98:99], v68, v95, s[98:99]
	v_cmp_le_u32_e64 s[98:99], s0, v4
	v_addc_co_u32_e64 v68, s[100:101], v68, v97, s[100:101]
	v_cmp_le_u32_e64 s[100:101], s0, v14
	v_addc_co_u32_e32 v68, vcc, v68, v99, vcc
	v_cmp_le_u32_e32 vcc, s0, v11
	v_addc_co_u32_e64 v67, s[98:99], v68, v67, s[98:99]
	v_cmp_le_u32_e64 s[98:99], s0, v25
	v_addc_co_u32_e64 v67, s[100:101], v67, v70, s[100:101]
	v_cmp_le_u32_e64 s[100:101], s0, v21
	v_addc_co_u32_e32 v67, vcc, v67, v72, vcc
	v_cmp_le_u32_e32 vcc, s0, v31
	v_addc_co_u32_e64 v67, s[98:99], v67, v74, s[98:99]
	v_cmp_le_u32_e64 s[98:99], s0, v20
	v_addc_co_u32_e64 v67, s[100:101], v67, v76, s[100:101]
	v_cmp_le_u32_e64 s[100:101], s0, v32
	v_addc_co_u32_e32 v67, vcc, v67, v78, vcc
	v_cmp_le_u32_e32 vcc, s0, v33
	v_addc_co_u32_e64 v67, s[98:99], v67, v80, s[98:99]
	v_cmp_le_u32_e64 s[98:99], s0, v44
	v_addc_co_u32_e64 v67, s[100:101], v67, v82, s[100:101]
	v_cmp_le_u32_e64 s[100:101], s0, v43
	v_addc_co_u32_e32 v67, vcc, v67, v84, vcc
	v_cmp_le_u32_e32 vcc, s0, v53
	v_addc_co_u32_e64 v67, s[98:99], v67, v86, s[98:99]
	v_cmp_le_u32_e64 s[98:99], s0, v50
	v_addc_co_u32_e64 v67, s[100:101], v67, v88, s[100:101]
	v_cmp_le_u32_e64 s[100:101], s0, v61
	v_addc_co_u32_e32 v67, vcc, v67, v90, vcc
	v_cmp_le_u32_e32 vcc, s0, v58
	v_addc_co_u32_e64 v67, s[98:99], v67, v92, s[98:99]
	v_cmp_le_u32_e64 s[98:99], s0, v65
	v_addc_co_u32_e64 v67, s[100:101], v67, v94, s[100:101]
	v_addc_co_u32_e32 v67, vcc, v67, v96, vcc
	v_addc_co_u32_e64 v67, s[98:99], v67, v98, s[98:99]
	s_nop 1
	v_add_u32_dpp v67, v67, v67 quad_perm:[1,0,3,2] row_mask:0xf bank_mask:0xf bound_ctrl:1
	s_nop 1
	v_add_u32_dpp v67, v67, v67 quad_perm:[2,3,0,1] row_mask:0xf bank_mask:0xf bound_ctrl:1
	s_nop 1
	v_add_u32_dpp v67, v67, v67 row_half_mirror row_mask:0xf bank_mask:0xf bound_ctrl:1
	s_nop 1
	v_add_u32_dpp v67, v67, v67 row_mirror row_mask:0xf bank_mask:0xf bound_ctrl:1
	s_nop 0
	v_readlane_b32 s1, v67, 0
	v_readlane_b32 s2, v67, 16
	v_readlane_b32 s3, v67, 32
	s_add_i32 s1, s2, s1
	v_readlane_b32 s4, v67, 48
	s_add_i32 s1, s1, s3
	s_add_i32 s1, s1, s4
	s_cmpk_lg_i32 s1, 0x100
	s_cselect_b64 s[2:3], -1, 0
	s_cmpk_gt_i32 s1, 0xff
	s_cselect_b32 s97, s0, s97
	s_add_i32 s0, s7, -1
	s_cmp_gt_i32 s7, 0
	s_mov_b32 s7, s0
	s_cselect_b64 s[0:1], -1, 0
	s_and_b64 s[0:1], s[2:3], s[0:1]
	s_and_b64 vcc, exec, s[0:1]
	s_cbranch_vccnz .LBB0_1173

; #define LAS __attribute__((address_space(3)))
; __global__ void __launch_bounds__(256, 2) mega(P p, int ph_lo, int ph_hi, int coop) {
;   __shared__ __attribute__((aligned(16))) char lds[LDS_BYTES];
;   __shared__ uint4 xb_words;
;   XcdBarrier xb;
;   if (coop) {
;     if (__builtin_amdgcn_workitem_id_x() == 0) xb_words = make_uint4(0u, 0u, 0u, 0u);
;     __syncthreads();
;     xb = xcd_barrier_post((unsigned*)(p.ws + W_BAR), (volatile LAS unsigned*)&xb_words);
;   }
;   for (int ph = ph_lo; ph < ph_hi; ++ph) {
;     run_phase(p, ph, lds);
;     if (coop && ph + 1 < ph_hi) {
;       if (coop == 2) cg::this_grid().sync();
;       xcd_barrier(xb);
;     }
;   }
; }
	.amdhsa_kernel _Z4mega1Piii
		.amdhsa_group_segment_fixed_size 68112
		.amdhsa_private_segment_fixed_size 0
		.amdhsa_kernarg_size 400
		.amdhsa_user_sgpr_count 2
		.amdhsa_user_sgpr_dispatch_ptr 0
		.amdhsa_user_sgpr_queue_ptr 0
		.amdhsa_user_sgpr_kernarg_segment_ptr 1
		.amdhsa_user_sgpr_dispatch_id 0
		.amdhsa_user_sgpr_kernarg_preload_length 0
		.amdhsa_user_sgpr_kernarg_preload_offset 0
		.amdhsa_user_sgpr_private_segment_size 0
		.amdhsa_uses_dynamic_stack 0
		.amdhsa_enable_private_segment 0
		.amdhsa_system_sgpr_workgroup_id_x 1
		.amdhsa_system_sgpr_workgroup_id_y 0
		.amdhsa_system_sgpr_workgroup_id_z 0
		.amdhsa_system_sgpr_workgroup_info 0
		.amdhsa_system_vgpr_workitem_id 2
		.amdhsa_next_free_vgpr 241
		.amdhsa_next_free_sgpr 102
		.amdhsa_accum_offset 244
		.amdhsa_reserve_vcc 1
		.amdhsa_float_round_mode_32 0
		.amdhsa_float_round_mode_16_64 0
		.amdhsa_float_denorm_mode_32 3
		.amdhsa_float_denorm_mode_16_64 3
		.amdhsa_dx10_clamp 1
		.amdhsa_ieee_mode 1
		.amdhsa_fp16_overflow 0
		.amdhsa_tg_split 0
		.amdhsa_exception_fp_ieee_invalid_op 0
		.amdhsa_exception_fp_denorm_src 0
		.amdhsa_exception_fp_ieee_div_zero 0
		.amdhsa_exception_fp_ieee_overflow 0
		.amdhsa_exception_fp_ieee_underflow 0
		.amdhsa_exception_fp_ieee_inexact 0
		.amdhsa_exception_int_div_zero 0
	.end_amdhsa_kernel

; #define LAS __attribute__((address_space(3)))
; __global__ void __launch_bounds__(256, 2) mega(P p, int ph_lo, int ph_hi, int coop) {
;   __shared__ __attribute__((aligned(16))) char lds[LDS_BYTES];
;   __shared__ uint4 xb_words;
;   XcdBarrier xb;
;   if (coop) {
;     if (__builtin_amdgcn_workitem_id_x() == 0) xb_words = make_uint4(0u, 0u, 0u, 0u);
;     __syncthreads();
;     xb = xcd_barrier_post((unsigned*)(p.ws + W_BAR), (volatile LAS unsigned*)&xb_words);
;   }
;   for (int ph = ph_lo; ph < ph_hi; ++ph) {
;     run_phase(p, ph, lds);
;     if (coop && ph + 1 < ph_hi) {
;       if (coop == 2) cg::this_grid().sync();
;       xcd_barrier(xb);
;     }
;   }
; }
amdhsa.kernels:
  - .agpr_count:     0
    .args:
      - .offset:         0
        .size:           128
        .value_kind:     by_value
      - .offset:         128
        .size:           4
        .value_kind:     by_value
      - .offset:         132
        .size:           4
        .value_kind:     by_value
      - .offset:         136
        .size:           4
        .value_kind:     by_value
      - .offset:         144
        .size:           4
        .value_kind:     hidden_block_count_x
      - .offset:         148
        .size:           4
        .value_kind:     hidden_block_count_y
      - .offset:         152
        .size:           4
        .value_kind:     hidden_block_count_z
      - .offset:         156
        .size:           2
        .value_kind:     hidden_group_size_x
      - .offset:         158
        .size:           2
        .value_kind:     hidden_group_size_y
      - .offset:         160
        .size:           2
        .value_kind:     hidden_group_size_z
      - .offset:         162
        .size:           2
        .value_kind:     hidden_remainder_x
      - .offset:         164
        .size:           2
        .value_kind:     hidden_remainder_y
      - .offset:         166
        .size:           2
        .value_kind:     hidden_remainder_z
      - .offset:         184
        .size:           8
        .value_kind:     hidden_global_offset_x
      - .offset:         192
        .size:           8
        .value_kind:     hidden_global_offset_y
      - .offset:         200
        .size:           8
        .value_kind:     hidden_global_offset_z
      - .offset:         208
        .size:           2
        .value_kind:     hidden_grid_dims
      - .offset:         232
        .size:           8
        .value_kind:     hidden_multigrid_sync_arg
    .group_segment_fixed_size: 68112
    .kernarg_segment_align: 8
    .kernarg_segment_size: 400
    .language:       OpenCL C
    .language_version:
      - 2
      - 0
    .max_flat_workgroup_size: 256
    .name:           _Z4mega1Piii
    .private_segment_fixed_size: 0
    .sgpr_count:     108
    .sgpr_spill_count: 523
    .symbol:         _Z4mega1Piii.kd
    .uniform_work_group_size: 1
    .uses_dynamic_stack: false
    .vgpr_count:     241
    .vgpr_spill_count: 0
    .wavefront_size: 64
